# out-proj epilogues (3 of 4): adjacent 16x16 blocks exchanged between lane halves (DPP on copies) so f32 stores write 8 rows x 128B and bf16 stores 8 rows x 64B (half the row segments); counted waits a
# speedup vs baseline: 1.0085x; 1.0085x over previous
.LBB0_522:
	s_mov_b32 s98, 0x10000
	s_mov_b32 s99, 0
	s_mov_b32 s100, 0x8000
	s_mov_b32 s101, 0
	v_bfe_u32 v255, v220, 3, 1
	v_sub_u32_e32 v255, 0, v255
	v_and_b32_e32 v254, 0xffff0040, v255
	v_lshl_add_u32 v168, s71, 8, v174
	v_lshl_or_b32 v164, s72, 8, v176
	v_readlane_b32 s72, v248, 9
	v_ashrrev_i32_e32 v165, 31, v164
	v_ashrrev_i32_e32 v169, 31, v168
	v_readlane_b32 s73, v248, 10
	v_lshlrev_b64 v[128:129], 13, v[168:169]
	v_readlane_b32 s74, v248, 11
	v_lshl_add_u64 v[166:167], v[164:165], 2, s[72:73]
	v_lshl_add_u64 v[128:129], v[166:167], 0, v[128:129]
	global_load_dwordx4 v[180:183], v[128:129], off
	global_load_dwordx4 v[184:187], v[128:129], off offset:64
	global_load_dwordx4 v[188:191], v[128:129], off offset:512
	global_load_dwordx4 v[192:195], v[128:129], off offset:576
	v_or_b32_e32 v128, 16, v168
	v_ashrrev_i32_e32 v129, 31, v128
	v_lshlrev_b64 v[130:131], 13, v[128:129]
	v_lshl_add_u64 v[130:131], v[166:167], 0, v[130:131]
	global_load_dwordx4 v[196:199], v[130:131], off
	global_load_dwordx4 v[200:203], v[130:131], off offset:64
	v_readlane_b32 s75, v248, 12
	v_readlane_b32 s76, v248, 13
	v_readlane_b32 s77, v248, 14
	v_readlane_b32 s78, v248, 15
	v_readlane_b32 s79, v248, 16
	v_or_b32_e32 v172, 32, v168
	v_readlane_b32 s72, v248, 0
	v_or_b32_e32 v170, 48, v168
	v_ashrrev_i32_e32 v173, 31, v172
	v_readlane_b32 s76, v248, 4
	v_readlane_b32 s77, v248, 5
	v_ashrrev_i32_e32 v171, 31, v170
	v_lshlrev_b64 v[132:133], 11, v[168:169]
	v_lshlrev_b64 v[134:135], 13, v[172:173]
	v_readlane_b32 s78, v248, 6
	v_readlane_b32 s79, v248, 7
	s_mov_b64 s[24:25], s[76:77]
	v_lshlrev_b64 v[136:137], 13, v[170:171]
	v_lshl_add_u64 v[132:133], v[132:133], 0, v[164:165]
	v_lshlrev_b64 v[128:129], 11, v[128:129]
	v_lshl_add_u64 v[134:135], v[166:167], 0, v[134:135]
	s_mov_b64 s[26:27], s[78:79]
	v_lshl_add_u64 v[226:227], v[166:167], 0, v[136:137]
	v_lshl_add_u64 v[228:229], v[132:133], 2, s[26:27]
	v_lshl_add_u64 v[230:231], v[132:133], 1, s[10:11]
	v_lshl_add_u64 v[232:233], v[128:129], 0, v[164:165]
	global_load_dwordx4 v[204:207], v[130:131], off offset:512
	global_load_dwordx4 v[208:211], v[130:131], off offset:576
	global_load_dwordx4 v[212:215], v[134:135], off
	global_load_dwordx4 v[216:219], v[134:135], off offset:64
	global_load_dwordx4 v[222:225], v[134:135], off offset:512
	global_load_dwordx4 v[144:147], v[134:135], off offset:576
	global_load_dwordx4 v[140:143], v[226:227], off
	global_load_dwordx4 v[136:139], v[226:227], off offset:64
	s_nop 0
	global_load_dwordx4 v[132:135], v[226:227], off offset:512
	global_load_dwordx4 v[128:131], v[226:227], off offset:576
	v_lshl_add_u64 v[226:227], v[232:233], 2, s[26:27]
	v_readlane_b32 s80, v248, 17
	v_readlane_b32 s81, v248, 18
	v_readlane_b32 s82, v248, 19
	v_readlane_b32 s83, v248, 20
	v_readlane_b32 s84, v248, 21
	v_readlane_b32 s85, v248, 22
	v_readlane_b32 s86, v248, 23
	v_readlane_b32 s87, v248, 24
	v_readlane_b32 s73, v248, 1
	v_readlane_b32 s74, v248, 2
	v_readlane_b32 s75, v248, 3
	s_waitcnt vmcnt(0)
	v_pk_add_f32 v[126:127], v[126:127], v[182:183]
	v_pk_add_f32 v[124:125], v[124:125], v[180:181]
	v_pk_add_f32 v[120:121], v[120:121], v[184:185]
	v_pk_add_f32 v[122:123], v[122:123], v[186:187]
	v_pk_add_f32 v[112:113], v[112:113], v[188:189]
	v_mov_b32_e32 v240, v124
	v_mov_b32_e32 v241, v125
	v_mov_b32_e32 v242, v126
	v_mov_b32_e32 v243, v127
	v_mul_f32_e32 v182, v125, v125
	v_cvt_pk_bf16_f32 v180, v124, v125
	v_cvt_pk_bf16_f32 v181, v126, v127
	v_pk_add_f32 v[114:115], v[114:115], v[190:191]
	v_mul_f32_e32 v125, v121, v121
	v_pk_add_f32 v[108:109], v[108:109], v[192:193]
	v_mul_f32_e32 v183, v127, v127
	v_mul_f32_e32 v127, v123, v123
	v_mul_f32_e32 v184, v113, v113
	v_mov_b32_e32 v244, v120
	v_mov_b32_e32 v245, v121
	v_mov_b32_e32 v246, v122
	v_mov_b32_e32 v247, v123
	v_mov_b32_dpp v244, v240 row_ror:8 row_mask:0xf bank_mask:0x3
	v_mov_b32_dpp v245, v241 row_ror:8 row_mask:0xf bank_mask:0x3
	v_mov_b32_dpp v246, v242 row_ror:8 row_mask:0xf bank_mask:0x3
	v_mov_b32_dpp v247, v243 row_ror:8 row_mask:0xf bank_mask:0x3
	v_mov_b32_dpp v240, v120 row_ror:8 row_mask:0xf bank_mask:0xc
	v_mov_b32_dpp v241, v121 row_ror:8 row_mask:0xf bank_mask:0xc
	v_mov_b32_dpp v242, v122 row_ror:8 row_mask:0xf bank_mask:0xc
	v_mov_b32_dpp v243, v123 row_ror:8 row_mask:0xf bank_mask:0xc
	v_lshl_add_u64 v[250:251], v[228:229], 0, v[254:255]
	v_lshl_add_u64 v[252:253], v[250:251], 0, s[98:99]
	global_store_dwordx4 v[250:251], v[240:243], off
	global_store_dwordx4 v[252:253], v[244:247], off
	v_ashrrev_i64 v[250:251], 1, v[254:255]
	v_lshl_add_u64 v[250:251], v[230:231], 0, v[250:251]
	v_lshl_add_u64 v[252:253], v[250:251], 0, s[100:101]
	v_cvt_pk_bf16_f32 v240, v240, v241
	v_cvt_pk_bf16_f32 v241, v242, v243
	v_cvt_pk_bf16_f32 v244, v244, v245
	v_cvt_pk_bf16_f32 v245, v246, v247
	global_store_dwordx2 v[250:251], v[240:241], off
	global_store_dwordx2 v[252:253], v[244:245], off
	v_fmac_f32_e32 v125, v120, v120
	v_pk_add_f32 v[110:111], v[110:111], v[194:195]
	v_cvt_pk_bf16_f32 v120, v120, v121
	v_cvt_pk_bf16_f32 v121, v122, v123
	v_mul_f32_e32 v185, v115, v115
	v_mul_f32_e32 v186, v109, v109
	v_fmac_f32_e32 v182, v124, v124
	v_fmac_f32_e32 v183, v126, v126
	v_fmac_f32_e32 v127, v122, v122
	v_fmac_f32_e32 v184, v112, v112
	v_mov_b32_e32 v240, v112
	v_mov_b32_e32 v241, v113
	v_mov_b32_e32 v242, v114
	v_mov_b32_e32 v243, v115
	v_mul_f32_e32 v187, v111, v111
	v_pk_add_f32 v[118:119], v[118:119], v[198:199]
	v_cvt_pk_bf16_f32 v112, v112, v113
	v_cvt_pk_bf16_f32 v113, v114, v115
	v_pk_add_f32 v[116:117], v[116:117], v[196:197]
	v_fmac_f32_e32 v185, v114, v114
	v_fmac_f32_e32 v186, v108, v108
	v_add_f32_e32 v122, v182, v183
	v_add_f32_e32 v123, v125, v127
	v_mov_b32_e32 v244, v108
	v_mov_b32_e32 v245, v109
	v_mov_b32_e32 v246, v110
	v_mov_b32_e32 v247, v111
	v_mov_b32_dpp v244, v240 row_ror:8 row_mask:0xf bank_mask:0x3
	v_mov_b32_dpp v245, v241 row_ror:8 row_mask:0xf bank_mask:0x3
	v_mov_b32_dpp v246, v242 row_ror:8 row_mask:0xf bank_mask:0x3
	v_mov_b32_dpp v247, v243 row_ror:8 row_mask:0xf bank_mask:0x3
	v_mov_b32_dpp v240, v108 row_ror:8 row_mask:0xf bank_mask:0xc
	v_mov_b32_dpp v241, v109 row_ror:8 row_mask:0xf bank_mask:0xc
	v_mov_b32_dpp v242, v110 row_ror:8 row_mask:0xf bank_mask:0xc
	v_mov_b32_dpp v243, v111 row_ror:8 row_mask:0xf bank_mask:0xc
	v_lshl_add_u64 v[250:251], v[228:229], 0, v[254:255]
	v_lshl_add_u64 v[252:253], v[250:251], 0, s[98:99]
	global_store_dwordx4 v[250:251], v[240:243], off offset:512
	global_store_dwordx4 v[252:253], v[244:247], off offset:512
	v_ashrrev_i64 v[250:251], 1, v[254:255]
	v_lshl_add_u64 v[250:251], v[230:231], 0, v[250:251]
	v_lshl_add_u64 v[252:253], v[250:251], 0, s[100:101]
	v_cvt_pk_bf16_f32 v240, v240, v241
	v_cvt_pk_bf16_f32 v241, v242, v243
	v_cvt_pk_bf16_f32 v244, v244, v245
	v_cvt_pk_bf16_f32 v245, v246, v247
	global_store_dwordx2 v[250:251], v[240:241], off offset:256
	global_store_dwordx2 v[252:253], v[244:245], off offset:256
	v_fmac_f32_e32 v187, v110, v110
	v_add_f32_e32 v120, v184, v185
	v_cvt_pk_bf16_f32 v108, v108, v109
	v_cvt_pk_bf16_f32 v109, v110, v111
	v_add_f32_e32 v115, v122, v123
	v_mul_f32_e32 v108, v117, v117
	v_mul_f32_e32 v109, v119, v119
	v_add_f32_e32 v114, v186, v187
	v_add_f32_e32 v110, v115, v120
	v_fmac_f32_e32 v108, v116, v116
	v_fmac_f32_e32 v109, v118, v118
	v_add_f32_e32 v112, v110, v114
	v_mov_b32_e32 v240, v116
	v_mov_b32_e32 v241, v117
	v_mov_b32_e32 v242, v118
	v_mov_b32_e32 v243, v119
	v_add_f32_e32 v113, v108, v109
	v_cvt_pk_bf16_f32 v108, v116, v117
	v_lshl_add_u64 v[110:111], v[232:233], 1, s[10:11]
	v_pk_add_f32 v[104:105], v[104:105], v[200:201]
	v_cvt_pk_bf16_f32 v109, v118, v119
	v_pk_add_f32 v[106:107], v[106:107], v[202:203]
	v_mul_f32_e32 v108, v105, v105
	v_mov_b32_e32 v244, v104
	v_mov_b32_e32 v245, v105
	v_mov_b32_e32 v246, v106
	v_mov_b32_e32 v247, v107
	v_mov_b32_dpp v244, v240 row_ror:8 row_mask:0xf bank_mask:0x3
	v_mov_b32_dpp v245, v241 row_ror:8 row_mask:0xf bank_mask:0x3
	v_mov_b32_dpp v246, v242 row_ror:8 row_mask:0xf bank_mask:0x3
	v_mov_b32_dpp v247, v243 row_ror:8 row_mask:0xf bank_mask:0x3
	v_mov_b32_dpp v240, v104 row_ror:8 row_mask:0xf bank_mask:0xc
	v_mov_b32_dpp v241, v105 row_ror:8 row_mask:0xf bank_mask:0xc
	v_mov_b32_dpp v242, v106 row_ror:8 row_mask:0xf bank_mask:0xc
	v_mov_b32_dpp v243, v107 row_ror:8 row_mask:0xf bank_mask:0xc
	v_lshl_add_u64 v[250:251], v[226:227], 0, v[254:255]
	v_lshl_add_u64 v[252:253], v[250:251], 0, s[98:99]
	global_store_dwordx4 v[250:251], v[240:243], off
	global_store_dwordx4 v[252:253], v[244:247], off
	v_ashrrev_i64 v[250:251], 1, v[254:255]
	v_lshl_add_u64 v[250:251], v[110:111], 0, v[250:251]
	v_lshl_add_u64 v[252:253], v[250:251], 0, s[100:101]
	v_cvt_pk_bf16_f32 v240, v240, v241
	v_cvt_pk_bf16_f32 v241, v242, v243
	v_cvt_pk_bf16_f32 v244, v244, v245
	v_cvt_pk_bf16_f32 v245, v246, v247
	global_store_dwordx2 v[250:251], v[240:241], off
	global_store_dwordx2 v[252:253], v[244:245], off
	v_fmac_f32_e32 v108, v104, v104
	v_pk_add_f32 v[100:101], v[100:101], v[204:205]
	v_cvt_pk_bf16_f32 v104, v104, v105
	v_cvt_pk_bf16_f32 v105, v106, v107
	v_pk_add_f32 v[102:103], v[102:103], v[206:207]
	v_mul_f32_e32 v104, v101, v101
	v_mov_b32_e32 v240, v100
	v_mov_b32_e32 v241, v101
	v_mov_b32_e32 v242, v102
	v_mov_b32_e32 v243, v103
	v_fmac_f32_e32 v104, v100, v100
	v_pk_add_f32 v[96:97], v[96:97], v[208:209]
	v_cvt_pk_bf16_f32 v100, v100, v101
	v_cvt_pk_bf16_f32 v101, v102, v103
	v_pk_add_f32 v[98:99], v[98:99], v[210:211]
	v_mul_f32_e32 v100, v97, v97
	v_mov_b32_e32 v244, v96
	v_mov_b32_e32 v245, v97
	v_mov_b32_e32 v246, v98
	v_mov_b32_e32 v247, v99
	v_mov_b32_dpp v244, v240 row_ror:8 row_mask:0xf bank_mask:0x3
	v_mov_b32_dpp v245, v241 row_ror:8 row_mask:0xf bank_mask:0x3
	v_mov_b32_dpp v246, v242 row_ror:8 row_mask:0xf bank_mask:0x3
	v_mov_b32_dpp v247, v243 row_ror:8 row_mask:0xf bank_mask:0x3
	v_mov_b32_dpp v240, v96 row_ror:8 row_mask:0xf bank_mask:0xc
	v_mov_b32_dpp v241, v97 row_ror:8 row_mask:0xf bank_mask:0xc
	v_mov_b32_dpp v242, v98 row_ror:8 row_mask:0xf bank_mask:0xc
	v_mov_b32_dpp v243, v99 row_ror:8 row_mask:0xf bank_mask:0xc
	v_lshl_add_u64 v[250:251], v[226:227], 0, v[254:255]
	v_lshl_add_u64 v[252:253], v[250:251], 0, s[98:99]
	global_store_dwordx4 v[250:251], v[240:243], off offset:512
	global_store_dwordx4 v[252:253], v[244:247], off offset:512
	v_ashrrev_i64 v[250:251], 1, v[254:255]
	v_lshl_add_u64 v[250:251], v[110:111], 0, v[250:251]
	v_lshl_add_u64 v[252:253], v[250:251], 0, s[100:101]
	v_cvt_pk_bf16_f32 v240, v240, v241
	v_cvt_pk_bf16_f32 v241, v242, v243
	v_cvt_pk_bf16_f32 v244, v244, v245
	v_cvt_pk_bf16_f32 v245, v246, v247
	global_store_dwordx2 v[250:251], v[240:241], off offset:256
	global_store_dwordx2 v[252:253], v[244:245], off offset:256
	v_fmac_f32_e32 v100, v96, v96
	v_mul_f32_e32 v101, v99, v99
	v_cvt_pk_bf16_f32 v96, v96, v97
	v_cvt_pk_bf16_f32 v97, v98, v99
	v_lshlrev_b64 v[96:97], 11, v[172:173]
	v_mul_f32_e32 v105, v103, v103
	v_fmac_f32_e32 v101, v98, v98
	v_lshl_add_u64 v[96:97], v[96:97], 0, v[164:165]
	v_pk_add_f32 v[94:95], v[94:95], v[214:215]
	v_pk_add_f32 v[92:93], v[92:93], v[212:213]
	v_fmac_f32_e32 v105, v102, v102
	v_add_f32_e32 v100, v100, v101
	v_lshl_add_u64 v[98:99], v[96:97], 2, s[26:27]
	v_mul_f32_e32 v101, v93, v93
	v_mul_f32_e32 v102, v95, v95
	v_mov_b32_e32 v240, v92
	v_mov_b32_e32 v241, v93
	v_mov_b32_e32 v242, v94
	v_mov_b32_e32 v243, v95
	v_fmac_f32_e32 v101, v92, v92
	v_fmac_f32_e32 v102, v94, v94
	v_cvt_pk_bf16_f32 v92, v92, v93
	v_cvt_pk_bf16_f32 v93, v94, v95
	v_lshl_add_u64 v[94:95], v[96:97], 1, s[10:11]
	v_pk_add_f32 v[88:89], v[88:89], v[216:217]
	v_pk_add_f32 v[90:91], v[90:91], v[218:219]
	v_mul_f32_e32 v92, v89, v89
	v_mov_b32_e32 v244, v88
	v_mov_b32_e32 v245, v89
	v_mov_b32_e32 v246, v90
	v_mov_b32_e32 v247, v91
	v_mov_b32_dpp v244, v240 row_ror:8 row_mask:0xf bank_mask:0x3
	v_mov_b32_dpp v245, v241 row_ror:8 row_mask:0xf bank_mask:0x3
	v_mov_b32_dpp v246, v242 row_ror:8 row_mask:0xf bank_mask:0x3
	v_mov_b32_dpp v247, v243 row_ror:8 row_mask:0xf bank_mask:0x3
	v_mov_b32_dpp v240, v88 row_ror:8 row_mask:0xf bank_mask:0xc
	v_mov_b32_dpp v241, v89 row_ror:8 row_mask:0xf bank_mask:0xc
	v_mov_b32_dpp v242, v90 row_ror:8 row_mask:0xf bank_mask:0xc
	v_mov_b32_dpp v243, v91 row_ror:8 row_mask:0xf bank_mask:0xc
	v_lshl_add_u64 v[250:251], v[98:99], 0, v[254:255]
	v_lshl_add_u64 v[252:253], v[250:251], 0, s[98:99]
	global_store_dwordx4 v[250:251], v[240:243], off
	global_store_dwordx4 v[252:253], v[244:247], off
	v_ashrrev_i64 v[250:251], 1, v[254:255]
	v_lshl_add_u64 v[250:251], v[94:95], 0, v[250:251]
	v_lshl_add_u64 v[252:253], v[250:251], 0, s[100:101]
	v_cvt_pk_bf16_f32 v240, v240, v241
	v_cvt_pk_bf16_f32 v241, v242, v243
	v_cvt_pk_bf16_f32 v244, v244, v245
	v_cvt_pk_bf16_f32 v245, v246, v247
	global_store_dwordx2 v[250:251], v[240:241], off
	global_store_dwordx2 v[252:253], v[244:245], off
	v_fmac_f32_e32 v92, v88, v88
	v_pk_add_f32 v[84:85], v[84:85], v[222:223]
	v_cvt_pk_bf16_f32 v88, v88, v89
	v_cvt_pk_bf16_f32 v89, v90, v91
	v_pk_add_f32 v[86:87], v[86:87], v[224:225]
	v_mul_f32_e32 v88, v85, v85
	v_mov_b32_e32 v240, v84
	v_mov_b32_e32 v241, v85
	v_mov_b32_e32 v242, v86
	v_mov_b32_e32 v243, v87
	v_fmac_f32_e32 v88, v84, v84
	v_pk_add_f32 v[80:81], v[80:81], v[144:145]
	v_cvt_pk_bf16_f32 v84, v84, v85
	v_cvt_pk_bf16_f32 v85, v86, v87
	v_pk_add_f32 v[82:83], v[82:83], v[146:147]
	v_mul_f32_e32 v84, v81, v81
	v_mov_b32_e32 v244, v80
	v_mov_b32_e32 v245, v81
	v_mov_b32_e32 v246, v82
	v_mov_b32_e32 v247, v83
	v_mov_b32_dpp v244, v240 row_ror:8 row_mask:0xf bank_mask:0x3
	v_mov_b32_dpp v245, v241 row_ror:8 row_mask:0xf bank_mask:0x3
	v_mov_b32_dpp v246, v242 row_ror:8 row_mask:0xf bank_mask:0x3
	v_mov_b32_dpp v247, v243 row_ror:8 row_mask:0xf bank_mask:0x3
	v_mov_b32_dpp v240, v80 row_ror:8 row_mask:0xf bank_mask:0xc
	v_mov_b32_dpp v241, v81 row_ror:8 row_mask:0xf bank_mask:0xc
	v_mov_b32_dpp v242, v82 row_ror:8 row_mask:0xf bank_mask:0xc
	v_mov_b32_dpp v243, v83 row_ror:8 row_mask:0xf bank_mask:0xc
	v_lshl_add_u64 v[250:251], v[98:99], 0, v[254:255]
	v_lshl_add_u64 v[252:253], v[250:251], 0, s[98:99]
	global_store_dwordx4 v[250:251], v[240:243], off offset:512
	global_store_dwordx4 v[252:253], v[244:247], off offset:512
	v_ashrrev_i64 v[250:251], 1, v[254:255]
	v_lshl_add_u64 v[250:251], v[94:95], 0, v[250:251]
	v_lshl_add_u64 v[252:253], v[250:251], 0, s[100:101]
	v_cvt_pk_bf16_f32 v240, v240, v241
	v_cvt_pk_bf16_f32 v241, v242, v243
	v_cvt_pk_bf16_f32 v244, v244, v245
	v_cvt_pk_bf16_f32 v245, v246, v247
	global_store_dwordx2 v[250:251], v[240:241], off offset:256
	global_store_dwordx2 v[252:253], v[244:245], off offset:256
	v_fmac_f32_e32 v84, v80, v80
	v_mul_f32_e32 v85, v83, v83
	v_cvt_pk_bf16_f32 v80, v80, v81
	v_cvt_pk_bf16_f32 v81, v82, v83
	v_lshlrev_b64 v[80:81], 11, v[170:171]
	v_mul_f32_e32 v89, v87, v87
	v_fmac_f32_e32 v85, v82, v82
	v_lshl_add_u64 v[80:81], v[80:81], 0, v[164:165]
	v_pk_add_f32 v[78:79], v[78:79], v[142:143]
	v_pk_add_f32 v[76:77], v[76:77], v[140:141]
	v_fmac_f32_e32 v89, v86, v86
	v_add_f32_e32 v84, v84, v85
	v_lshl_add_u64 v[82:83], v[80:81], 2, s[26:27]
	v_mul_f32_e32 v85, v77, v77
	v_mul_f32_e32 v86, v79, v79
	v_mov_b32_e32 v240, v76
	v_mov_b32_e32 v241, v77
	v_mov_b32_e32 v242, v78
	v_mov_b32_e32 v243, v79
	v_fmac_f32_e32 v85, v76, v76
	v_fmac_f32_e32 v86, v78, v78
	v_cvt_pk_bf16_f32 v76, v76, v77
	v_cvt_pk_bf16_f32 v77, v78, v79
	v_lshl_add_u64 v[78:79], v[80:81], 1, s[10:11]
	v_pk_add_f32 v[72:73], v[72:73], v[136:137]
	v_pk_add_f32 v[74:75], v[74:75], v[138:139]
	v_mul_f32_e32 v76, v73, v73
	v_mov_b32_e32 v244, v72
	v_mov_b32_e32 v245, v73
	v_mov_b32_e32 v246, v74
	v_mov_b32_e32 v247, v75
	v_mov_b32_dpp v244, v240 row_ror:8 row_mask:0xf bank_mask:0x3
	v_mov_b32_dpp v245, v241 row_ror:8 row_mask:0xf bank_mask:0x3
	v_mov_b32_dpp v246, v242 row_ror:8 row_mask:0xf bank_mask:0x3
	v_mov_b32_dpp v247, v243 row_ror:8 row_mask:0xf bank_mask:0x3
	v_mov_b32_dpp v240, v72 row_ror:8 row_mask:0xf bank_mask:0xc
	v_mov_b32_dpp v241, v73 row_ror:8 row_mask:0xf bank_mask:0xc
	v_mov_b32_dpp v242, v74 row_ror:8 row_mask:0xf bank_mask:0xc
	v_mov_b32_dpp v243, v75 row_ror:8 row_mask:0xf bank_mask:0xc
	v_lshl_add_u64 v[250:251], v[82:83], 0, v[254:255]
	v_lshl_add_u64 v[252:253], v[250:251], 0, s[98:99]
	global_store_dwordx4 v[250:251], v[240:243], off
	global_store_dwordx4 v[252:253], v[244:247], off
	v_ashrrev_i64 v[250:251], 1, v[254:255]
	v_lshl_add_u64 v[250:251], v[78:79], 0, v[250:251]
	v_lshl_add_u64 v[252:253], v[250:251], 0, s[100:101]
	v_cvt_pk_bf16_f32 v240, v240, v241
	v_cvt_pk_bf16_f32 v241, v242, v243
	v_cvt_pk_bf16_f32 v244, v244, v245
	v_cvt_pk_bf16_f32 v245, v246, v247
	global_store_dwordx2 v[250:251], v[240:241], off
	global_store_dwordx2 v[252:253], v[244:245], off
	v_fmac_f32_e32 v76, v72, v72
	v_mul_f32_e32 v77, v75, v75
	v_cvt_pk_bf16_f32 v72, v72, v73
	v_cvt_pk_bf16_f32 v73, v74, v75
	v_pk_add_f32 v[70:71], v[70:71], v[134:135]
	v_pk_add_f32 v[68:69], v[68:69], v[132:133]
	v_fmac_f32_e32 v77, v74, v74
	v_mul_f32_e32 v72, v69, v69
	v_mul_f32_e32 v73, v71, v71
	v_add_f32_e32 v85, v85, v86
	v_add_f32_e32 v76, v76, v77
	v_fmac_f32_e32 v72, v68, v68
	v_fmac_f32_e32 v73, v70, v70
	v_add_f32_e32 v76, v85, v76
	v_add_f32_e32 v72, v72, v73
	v_add_f32_e32 v76, v76, v72
	v_pk_add_f32 v[74:75], v[66:67], v[130:131]
	v_pk_add_f32 v[72:73], v[64:65], v[128:129]
	v_mul_f32_e32 v65, v75, v75
	v_mul_f32_e32 v64, v73, v73
	v_fmac_f32_e32 v64, v72, v72
	v_fmac_f32_e32 v65, v74, v74
	v_mov_b32_e32 v240, v68
	v_mov_b32_e32 v241, v69
	v_mov_b32_e32 v242, v70
	v_mov_b32_e32 v243, v71
	v_add_f32_e32 v64, v64, v65
	v_and_b32_e32 v65, 64, v179
	v_cvt_pk_bf16_f32 v68, v68, v69
	v_cvt_pk_bf16_f32 v69, v70, v71
	v_add_f32_e32 v67, v76, v64
	v_xor_b32_e32 v64, 16, v179
	v_add_u32_e32 v68, 64, v65
	v_mul_f32_e32 v109, v107, v107
	v_mul_f32_e32 v93, v91, v91
	v_cmp_lt_i32_e32 vcc, v64, v68
	v_fmac_f32_e32 v109, v106, v106
	v_fmac_f32_e32 v93, v90, v90
	v_cndmask_b32_e32 v64, v179, v64, vcc
	v_add_f32_e32 v108, v108, v109
	v_add_f32_e32 v101, v101, v102
	v_add_f32_e32 v92, v92, v93
	v_lshlrev_b32_e32 v90, 2, v64
	v_add_f32_e32 v108, v113, v108
	v_add_f32_e32 v104, v104, v105
	v_add_f32_e32 v92, v101, v92
	v_add_f32_e32 v88, v88, v89
	ds_bpermute_b32 v69, v90, v67
	v_add_f32_e32 v104, v108, v104
	v_add_f32_e32 v88, v92, v88
	v_add_f32_e32 v100, v104, v100
	v_add_f32_e32 v84, v88, v84
	ds_bpermute_b32 v64, v90, v112
	ds_bpermute_b32 v65, v90, v100
	ds_bpermute_b32 v66, v90, v84
	s_waitcnt lgkmcnt(3)
	v_add_f32_e32 v67, v67, v69
	v_xor_b32_e32 v69, 32, v179
	v_cmp_lt_i32_e32 vcc, v69, v68
	s_waitcnt lgkmcnt(2)
	v_add_f32_e32 v64, v112, v64
	s_waitcnt lgkmcnt(1)
	v_add_f32_e32 v65, v100, v65
	v_cndmask_b32_e32 v68, v179, v69, vcc
	s_waitcnt lgkmcnt(0)
	v_add_f32_e32 v66, v84, v66
	v_lshlrev_b32_e32 v91, 2, v68
	ds_bpermute_b32 v68, v91, v64
	ds_bpermute_b32 v69, v91, v65
	ds_bpermute_b32 v70, v91, v66
	ds_bpermute_b32 v71, v91, v67
	v_lshl_add_u64 v[84:85], v[168:169], 2, s[12:13]
	v_mov_b32_e32 v244, v72
	v_mov_b32_e32 v245, v73
	v_mov_b32_e32 v246, v74
	v_mov_b32_e32 v247, v75
	v_mov_b32_dpp v244, v240 row_ror:8 row_mask:0xf bank_mask:0x3
	v_mov_b32_dpp v245, v241 row_ror:8 row_mask:0xf bank_mask:0x3
	v_mov_b32_dpp v246, v242 row_ror:8 row_mask:0xf bank_mask:0x3
	v_mov_b32_dpp v247, v243 row_ror:8 row_mask:0xf bank_mask:0x3
	v_mov_b32_dpp v240, v72 row_ror:8 row_mask:0xf bank_mask:0xc
	v_mov_b32_dpp v241, v73 row_ror:8 row_mask:0xf bank_mask:0xc
	v_mov_b32_dpp v242, v74 row_ror:8 row_mask:0xf bank_mask:0xc
	v_mov_b32_dpp v243, v75 row_ror:8 row_mask:0xf bank_mask:0xc
	v_lshl_add_u64 v[250:251], v[82:83], 0, v[254:255]
	v_lshl_add_u64 v[252:253], v[250:251], 0, s[98:99]
	global_store_dwordx4 v[250:251], v[240:243], off offset:512
	global_store_dwordx4 v[252:253], v[244:247], off offset:512
	v_ashrrev_i64 v[250:251], 1, v[254:255]
	v_lshl_add_u64 v[250:251], v[78:79], 0, v[250:251]
	v_lshl_add_u64 v[252:253], v[250:251], 0, s[100:101]
	v_cvt_pk_bf16_f32 v240, v240, v241
	v_cvt_pk_bf16_f32 v241, v242, v243
	v_cvt_pk_bf16_f32 v244, v244, v245
	v_cvt_pk_bf16_f32 v245, v246, v247
	global_store_dwordx2 v[250:251], v[240:241], off offset:256
	global_store_dwordx2 v[252:253], v[244:245], off offset:256
	s_nop 1
	v_cvt_pk_bf16_f32 v72, v72, v73
	v_cvt_pk_bf16_f32 v73, v74, v75
	s_and_saveexec_b64 s[6:7], s[2:3]
	s_cbranch_execz .LBB0_524
	s_waitcnt lgkmcnt(3)
	v_add_f32_e32 v64, v64, v68
	s_waitcnt lgkmcnt(0)
	v_add_f32_e32 v67, v67, v71
	v_add_f32_e32 v66, v66, v70
	v_add_f32_e32 v65, v65, v69
	global_atomic_add_f32 v[84:85], v64, off
	global_atomic_add_f32 v[84:85], v65, off offset:64
	global_atomic_add_f32 v[84:85], v66, off offset:128
	global_atomic_add_f32 v[84:85], v67, off offset:192
.LBB0_524:
	s_or_b64 exec, exec, s[6:7]
	v_add_u32_e32 v64, 0x80, v168
	v_ashrrev_i32_e32 v65, 31, v64
	v_lshlrev_b64 v[66:67], 13, v[64:65]
	v_lshl_add_u64 v[66:67], v[166:167], 0, v[66:67]
	global_load_dwordx4 v[92:95], v[66:67], off
	global_load_dwordx4 v[96:99], v[66:67], off offset:64
	s_waitcnt lgkmcnt(3)
	v_add_u32_e32 v68, 0x90, v168
	s_waitcnt lgkmcnt(2)
	v_ashrrev_i32_e32 v69, 31, v68
	global_load_dwordx4 v[100:103], v[66:67], off offset:512
	global_load_dwordx4 v[104:107], v[66:67], off offset:576
	s_waitcnt lgkmcnt(0)
	v_lshlrev_b64 v[70:71], 13, v[68:69]
	v_lshl_add_u64 v[66:67], v[166:167], 0, v[70:71]
	global_load_dwordx4 v[108:111], v[66:67], off
	global_load_dwordx4 v[112:115], v[66:67], off offset:64
	v_add_u32_e32 v88, 0xa0, v168
	v_add_u32_e32 v86, 0xb0, v168
	v_ashrrev_i32_e32 v89, 31, v88
	v_ashrrev_i32_e32 v87, 31, v86
	v_lshlrev_b64 v[70:71], 13, v[88:89]
	v_lshlrev_b64 v[72:73], 13, v[86:87]
	v_lshlrev_b64 v[64:65], 11, v[64:65]
	v_lshlrev_b64 v[68:69], 11, v[68:69]
	v_lshl_add_u64 v[70:71], v[166:167], 0, v[70:71]
	v_lshl_add_u64 v[136:137], v[166:167], 0, v[72:73]
	v_lshl_add_u64 v[138:139], v[64:65], 0, v[164:165]
	v_lshl_add_u64 v[140:141], v[68:69], 0, v[164:165]
	global_load_dwordx4 v[116:119], v[66:67], off offset:512
	global_load_dwordx4 v[120:123], v[66:67], off offset:576
	global_load_dwordx4 v[124:127], v[70:71], off
	global_load_dwordx4 v[128:131], v[70:71], off offset:64
	global_load_dwordx4 v[132:135], v[70:71], off offset:512
	global_load_dwordx4 v[80:83], v[70:71], off offset:576
	global_load_dwordx4 v[76:79], v[136:137], off
	global_load_dwordx4 v[72:75], v[136:137], off offset:64
	s_nop 0
	global_load_dwordx4 v[68:71], v[136:137], off offset:512
	global_load_dwordx4 v[64:67], v[136:137], off offset:576
	v_readlane_b32 s72, v248, 0
	v_readlane_b32 s76, v248, 4
	v_readlane_b32 s77, v248, 5
	v_readlane_b32 s78, v248, 6
	v_readlane_b32 s79, v248, 7
	s_mov_b64 s[24:25], s[76:77]
	s_mov_b64 s[26:27], s[78:79]
	v_lshl_add_u64 v[136:137], v[138:139], 2, s[26:27]
	v_lshl_add_u64 v[138:139], v[138:139], 1, s[10:11]
	v_lshl_add_u64 v[142:143], v[140:141], 2, s[26:27]
	v_readlane_b32 s73, v248, 1
	v_readlane_b32 s74, v248, 2
	v_readlane_b32 s75, v248, 3
	s_waitcnt vmcnt(15)
	v_pk_add_f32 v[62:63], v[62:63], v[94:95]
	v_pk_add_f32 v[60:61], v[60:61], v[92:93]
	s_waitcnt vmcnt(14)
	v_pk_add_f32 v[56:57], v[56:57], v[96:97]
	v_pk_add_f32 v[58:59], v[58:59], v[98:99]
	s_waitcnt vmcnt(13)
	v_pk_add_f32 v[48:49], v[48:49], v[100:101]
	v_mov_b32_e32 v240, v60
	v_mov_b32_e32 v241, v61
	v_mov_b32_e32 v242, v62
	v_mov_b32_e32 v243, v63
	v_mul_f32_e32 v94, v61, v61
	v_cvt_pk_bf16_f32 v92, v60, v61
	v_cvt_pk_bf16_f32 v93, v62, v63
	v_pk_add_f32 v[50:51], v[50:51], v[102:103]
	v_mul_f32_e32 v61, v57, v57
	s_waitcnt vmcnt(12)
	v_pk_add_f32 v[44:45], v[44:45], v[104:105]
	v_mul_f32_e32 v95, v63, v63
	v_mul_f32_e32 v63, v59, v59
	v_mul_f32_e32 v96, v49, v49
	v_mov_b32_e32 v244, v56
	v_mov_b32_e32 v245, v57
	v_mov_b32_e32 v246, v58
	v_mov_b32_e32 v247, v59
	v_mov_b32_dpp v244, v240 row_ror:8 row_mask:0xf bank_mask:0x3
	v_mov_b32_dpp v245, v241 row_ror:8 row_mask:0xf bank_mask:0x3
	v_mov_b32_dpp v246, v242 row_ror:8 row_mask:0xf bank_mask:0x3
	v_mov_b32_dpp v247, v243 row_ror:8 row_mask:0xf bank_mask:0x3
	v_mov_b32_dpp v240, v56 row_ror:8 row_mask:0xf bank_mask:0xc
	v_mov_b32_dpp v241, v57 row_ror:8 row_mask:0xf bank_mask:0xc
	v_mov_b32_dpp v242, v58 row_ror:8 row_mask:0xf bank_mask:0xc
	v_mov_b32_dpp v243, v59 row_ror:8 row_mask:0xf bank_mask:0xc
	v_lshl_add_u64 v[250:251], v[136:137], 0, v[254:255]
	v_lshl_add_u64 v[252:253], v[250:251], 0, s[98:99]
	global_store_dwordx4 v[250:251], v[240:243], off
	global_store_dwordx4 v[252:253], v[244:247], off
	v_ashrrev_i64 v[250:251], 1, v[254:255]
	v_lshl_add_u64 v[250:251], v[138:139], 0, v[250:251]
	v_lshl_add_u64 v[252:253], v[250:251], 0, s[100:101]
	v_cvt_pk_bf16_f32 v240, v240, v241
	v_cvt_pk_bf16_f32 v241, v242, v243
	v_cvt_pk_bf16_f32 v244, v244, v245
	v_cvt_pk_bf16_f32 v245, v246, v247
	global_store_dwordx2 v[250:251], v[240:241], off
	global_store_dwordx2 v[252:253], v[244:245], off
	v_fmac_f32_e32 v61, v56, v56
	v_pk_add_f32 v[46:47], v[46:47], v[106:107]
	v_cvt_pk_bf16_f32 v56, v56, v57
	v_cvt_pk_bf16_f32 v57, v58, v59
	v_mul_f32_e32 v97, v51, v51
	v_mul_f32_e32 v98, v45, v45
	v_fmac_f32_e32 v94, v60, v60
	v_fmac_f32_e32 v95, v62, v62
	v_fmac_f32_e32 v63, v58, v58
	v_fmac_f32_e32 v96, v48, v48
	v_mov_b32_e32 v240, v48
	v_mov_b32_e32 v241, v49
	v_mov_b32_e32 v242, v50
	v_mov_b32_e32 v243, v51
	s_waitcnt vmcnt(15)
	v_pk_add_f32 v[54:55], v[54:55], v[110:111]
	v_pk_add_f32 v[52:53], v[52:53], v[108:109]
	v_cvt_pk_bf16_f32 v48, v48, v49
	v_cvt_pk_bf16_f32 v49, v50, v51
	v_mul_f32_e32 v99, v47, v47
	v_fmac_f32_e32 v97, v50, v50
	v_fmac_f32_e32 v98, v44, v44
	v_add_f32_e32 v58, v94, v95
	v_add_f32_e32 v59, v61, v63
	v_mov_b32_e32 v244, v44
	v_mov_b32_e32 v245, v45
	v_mov_b32_e32 v246, v46
	v_mov_b32_e32 v247, v47
	v_mov_b32_dpp v244, v240 row_ror:8 row_mask:0xf bank_mask:0x3
	v_mov_b32_dpp v245, v241 row_ror:8 row_mask:0xf bank_mask:0x3
	v_mov_b32_dpp v246, v242 row_ror:8 row_mask:0xf bank_mask:0x3
	v_mov_b32_dpp v247, v243 row_ror:8 row_mask:0xf bank_mask:0x3
	v_mov_b32_dpp v240, v44 row_ror:8 row_mask:0xf bank_mask:0xc
	v_mov_b32_dpp v241, v45 row_ror:8 row_mask:0xf bank_mask:0xc
	v_mov_b32_dpp v242, v46 row_ror:8 row_mask:0xf bank_mask:0xc
	v_mov_b32_dpp v243, v47 row_ror:8 row_mask:0xf bank_mask:0xc
	v_lshl_add_u64 v[250:251], v[136:137], 0, v[254:255]
	v_lshl_add_u64 v[252:253], v[250:251], 0, s[98:99]
	global_store_dwordx4 v[250:251], v[240:243], off offset:512
	global_store_dwordx4 v[252:253], v[244:247], off offset:512
	v_ashrrev_i64 v[250:251], 1, v[254:255]
	v_lshl_add_u64 v[250:251], v[138:139], 0, v[250:251]
	v_lshl_add_u64 v[252:253], v[250:251], 0, s[100:101]
	v_cvt_pk_bf16_f32 v240, v240, v241
	v_cvt_pk_bf16_f32 v241, v242, v243
	v_cvt_pk_bf16_f32 v244, v244, v245
	v_cvt_pk_bf16_f32 v245, v246, v247
	global_store_dwordx2 v[250:251], v[240:241], off offset:256
	global_store_dwordx2 v[252:253], v[244:245], off offset:256
	v_mul_f32_e32 v100, v53, v53
	v_fmac_f32_e32 v99, v46, v46
	v_cvt_pk_bf16_f32 v44, v44, v45
	v_cvt_pk_bf16_f32 v45, v46, v47
	v_add_f32_e32 v56, v96, v97
	v_add_f32_e32 v51, v58, v59
	v_mov_b32_e32 v240, v52
	v_mov_b32_e32 v241, v53
	v_mov_b32_e32 v242, v54
	v_mov_b32_e32 v243, v55
	v_mul_f32_e32 v44, v55, v55
	v_fmac_f32_e32 v100, v52, v52
	v_add_f32_e32 v50, v98, v99
	v_add_f32_e32 v46, v51, v56
	v_fmac_f32_e32 v44, v54, v54
	v_add_f32_e32 v48, v46, v50
	v_add_f32_e32 v49, v100, v44
	v_cvt_pk_bf16_f32 v44, v52, v53
	v_lshl_add_u64 v[46:47], v[140:141], 1, s[10:11]
	s_waitcnt vmcnt(18)
	v_pk_add_f32 v[40:41], v[40:41], v[112:113]
	v_cvt_pk_bf16_f32 v45, v54, v55
	v_pk_add_f32 v[42:43], v[42:43], v[114:115]
	v_mul_f32_e32 v44, v41, v41
	v_mov_b32_e32 v244, v40
	v_mov_b32_e32 v245, v41
	v_mov_b32_e32 v246, v42
	v_mov_b32_e32 v247, v43
	v_mov_b32_dpp v244, v240 row_ror:8 row_mask:0xf bank_mask:0x3
	v_mov_b32_dpp v245, v241 row_ror:8 row_mask:0xf bank_mask:0x3
	v_mov_b32_dpp v246, v242 row_ror:8 row_mask:0xf bank_mask:0x3
	v_mov_b32_dpp v247, v243 row_ror:8 row_mask:0xf bank_mask:0x3
	v_mov_b32_dpp v240, v40 row_ror:8 row_mask:0xf bank_mask:0xc
	v_mov_b32_dpp v241, v41 row_ror:8 row_mask:0xf bank_mask:0xc
	v_mov_b32_dpp v242, v42 row_ror:8 row_mask:0xf bank_mask:0xc
	v_mov_b32_dpp v243, v43 row_ror:8 row_mask:0xf bank_mask:0xc
	v_lshl_add_u64 v[250:251], v[142:143], 0, v[254:255]
	v_lshl_add_u64 v[252:253], v[250:251], 0, s[98:99]
	global_store_dwordx4 v[250:251], v[240:243], off
	global_store_dwordx4 v[252:253], v[244:247], off
	v_ashrrev_i64 v[250:251], 1, v[254:255]
	v_lshl_add_u64 v[250:251], v[46:47], 0, v[250:251]
	v_lshl_add_u64 v[252:253], v[250:251], 0, s[100:101]
	v_cvt_pk_bf16_f32 v240, v240, v241
	v_cvt_pk_bf16_f32 v241, v242, v243
	v_cvt_pk_bf16_f32 v244, v244, v245
	v_cvt_pk_bf16_f32 v245, v246, v247
	global_store_dwordx2 v[250:251], v[240:241], off
	global_store_dwordx2 v[252:253], v[244:245], off
	v_fmac_f32_e32 v44, v40, v40
	s_waitcnt vmcnt(20)
	v_pk_add_f32 v[36:37], v[36:37], v[116:117]
	v_cvt_pk_bf16_f32 v40, v40, v41
	v_cvt_pk_bf16_f32 v41, v42, v43
	v_pk_add_f32 v[38:39], v[38:39], v[118:119]
	v_mul_f32_e32 v40, v37, v37
	v_mov_b32_e32 v240, v36
	v_mov_b32_e32 v241, v37
	v_mov_b32_e32 v242, v38
	v_mov_b32_e32 v243, v39
	v_fmac_f32_e32 v40, v36, v36
	s_waitcnt vmcnt(20)
	v_pk_add_f32 v[32:33], v[32:33], v[120:121]
	v_cvt_pk_bf16_f32 v36, v36, v37
	v_cvt_pk_bf16_f32 v37, v38, v39
	v_pk_add_f32 v[34:35], v[34:35], v[122:123]
	v_mul_f32_e32 v36, v33, v33
	v_mov_b32_e32 v244, v32
	v_mov_b32_e32 v245, v33
	v_mov_b32_e32 v246, v34
	v_mov_b32_e32 v247, v35
	v_mov_b32_dpp v244, v240 row_ror:8 row_mask:0xf bank_mask:0x3
	v_mov_b32_dpp v245, v241 row_ror:8 row_mask:0xf bank_mask:0x3
	v_mov_b32_dpp v246, v242 row_ror:8 row_mask:0xf bank_mask:0x3
	v_mov_b32_dpp v247, v243 row_ror:8 row_mask:0xf bank_mask:0x3
	v_mov_b32_dpp v240, v32 row_ror:8 row_mask:0xf bank_mask:0xc
	v_mov_b32_dpp v241, v33 row_ror:8 row_mask:0xf bank_mask:0xc
	v_mov_b32_dpp v242, v34 row_ror:8 row_mask:0xf bank_mask:0xc
	v_mov_b32_dpp v243, v35 row_ror:8 row_mask:0xf bank_mask:0xc
	v_lshl_add_u64 v[250:251], v[142:143], 0, v[254:255]
	v_lshl_add_u64 v[252:253], v[250:251], 0, s[98:99]
	global_store_dwordx4 v[250:251], v[240:243], off offset:512
	global_store_dwordx4 v[252:253], v[244:247], off offset:512
	v_ashrrev_i64 v[250:251], 1, v[254:255]
	v_lshl_add_u64 v[250:251], v[46:47], 0, v[250:251]
	v_lshl_add_u64 v[252:253], v[250:251], 0, s[100:101]
	v_cvt_pk_bf16_f32 v240, v240, v241
	v_cvt_pk_bf16_f32 v241, v242, v243
	v_cvt_pk_bf16_f32 v244, v244, v245
	v_cvt_pk_bf16_f32 v245, v246, v247
	global_store_dwordx2 v[250:251], v[240:241], off offset:256
	global_store_dwordx2 v[252:253], v[244:245], off offset:256
	v_fmac_f32_e32 v36, v32, v32
	v_mul_f32_e32 v37, v35, v35
	v_cvt_pk_bf16_f32 v32, v32, v33
	v_cvt_pk_bf16_f32 v33, v34, v35
	v_lshlrev_b64 v[32:33], 11, v[88:89]
	v_mul_f32_e32 v41, v39, v39
	v_fmac_f32_e32 v37, v34, v34
	v_lshl_add_u64 v[32:33], v[32:33], 0, v[164:165]
	s_waitcnt vmcnt(23)
	v_pk_add_f32 v[30:31], v[30:31], v[126:127]
	v_pk_add_f32 v[28:29], v[28:29], v[124:125]
	v_fmac_f32_e32 v41, v38, v38
	v_add_f32_e32 v36, v36, v37
	v_lshl_add_u64 v[34:35], v[32:33], 2, s[26:27]
	v_mul_f32_e32 v37, v29, v29
	v_mul_f32_e32 v38, v31, v31
	v_mov_b32_e32 v240, v28
	v_mov_b32_e32 v241, v29
	v_mov_b32_e32 v242, v30
	v_mov_b32_e32 v243, v31
	v_fmac_f32_e32 v37, v28, v28
	v_fmac_f32_e32 v38, v30, v30
	v_cvt_pk_bf16_f32 v28, v28, v29
	v_cvt_pk_bf16_f32 v29, v30, v31
	v_lshl_add_u64 v[30:31], v[32:33], 1, s[10:11]
	s_waitcnt vmcnt(22)
	v_pk_add_f32 v[24:25], v[24:25], v[128:129]
	v_pk_add_f32 v[26:27], v[26:27], v[130:131]
	v_mul_f32_e32 v28, v25, v25
	v_mov_b32_e32 v244, v24
	v_mov_b32_e32 v245, v25
	v_mov_b32_e32 v246, v26
	v_mov_b32_e32 v247, v27
	v_mov_b32_dpp v244, v240 row_ror:8 row_mask:0xf bank_mask:0x3
	v_mov_b32_dpp v245, v241 row_ror:8 row_mask:0xf bank_mask:0x3
	v_mov_b32_dpp v246, v242 row_ror:8 row_mask:0xf bank_mask:0x3
	v_mov_b32_dpp v247, v243 row_ror:8 row_mask:0xf bank_mask:0x3
	v_mov_b32_dpp v240, v24 row_ror:8 row_mask:0xf bank_mask:0xc
	v_mov_b32_dpp v241, v25 row_ror:8 row_mask:0xf bank_mask:0xc
	v_mov_b32_dpp v242, v26 row_ror:8 row_mask:0xf bank_mask:0xc
	v_mov_b32_dpp v243, v27 row_ror:8 row_mask:0xf bank_mask:0xc
	v_lshl_add_u64 v[250:251], v[34:35], 0, v[254:255]
	v_lshl_add_u64 v[252:253], v[250:251], 0, s[98:99]
	global_store_dwordx4 v[250:251], v[240:243], off
	global_store_dwordx4 v[252:253], v[244:247], off
	v_ashrrev_i64 v[250:251], 1, v[254:255]
	v_lshl_add_u64 v[250:251], v[30:31], 0, v[250:251]
	v_lshl_add_u64 v[252:253], v[250:251], 0, s[100:101]
	v_cvt_pk_bf16_f32 v240, v240, v241
	v_cvt_pk_bf16_f32 v241, v242, v243
	v_cvt_pk_bf16_f32 v244, v244, v245
	v_cvt_pk_bf16_f32 v245, v246, v247
	global_store_dwordx2 v[250:251], v[240:241], off
	global_store_dwordx2 v[252:253], v[244:245], off
	v_fmac_f32_e32 v28, v24, v24
	s_waitcnt vmcnt(24)
	v_pk_add_f32 v[20:21], v[20:21], v[132:133]
	v_cvt_pk_bf16_f32 v24, v24, v25
	v_cvt_pk_bf16_f32 v25, v26, v27
	v_pk_add_f32 v[22:23], v[22:23], v[134:135]
	v_mul_f32_e32 v24, v21, v21
	v_mov_b32_e32 v240, v20
	v_mov_b32_e32 v241, v21
	v_mov_b32_e32 v242, v22
	v_mov_b32_e32 v243, v23
	v_fmac_f32_e32 v24, v20, v20
	s_waitcnt vmcnt(24)
	v_pk_add_f32 v[16:17], v[16:17], v[80:81]
	v_cvt_pk_bf16_f32 v20, v20, v21
	v_cvt_pk_bf16_f32 v21, v22, v23
	v_pk_add_f32 v[18:19], v[18:19], v[82:83]
	v_mul_f32_e32 v20, v17, v17
	v_mov_b32_e32 v244, v16
	v_mov_b32_e32 v245, v17
	v_mov_b32_e32 v246, v18
	v_mov_b32_e32 v247, v19
	v_mov_b32_dpp v244, v240 row_ror:8 row_mask:0xf bank_mask:0x3
	v_mov_b32_dpp v245, v241 row_ror:8 row_mask:0xf bank_mask:0x3
	v_mov_b32_dpp v246, v242 row_ror:8 row_mask:0xf bank_mask:0x3
	v_mov_b32_dpp v247, v243 row_ror:8 row_mask:0xf bank_mask:0x3
	v_mov_b32_dpp v240, v16 row_ror:8 row_mask:0xf bank_mask:0xc
	v_mov_b32_dpp v241, v17 row_ror:8 row_mask:0xf bank_mask:0xc
	v_mov_b32_dpp v242, v18 row_ror:8 row_mask:0xf bank_mask:0xc
	v_mov_b32_dpp v243, v19 row_ror:8 row_mask:0xf bank_mask:0xc
	v_lshl_add_u64 v[250:251], v[34:35], 0, v[254:255]
	v_lshl_add_u64 v[252:253], v[250:251], 0, s[98:99]
	global_store_dwordx4 v[250:251], v[240:243], off offset:512
	global_store_dwordx4 v[252:253], v[244:247], off offset:512
	v_ashrrev_i64 v[250:251], 1, v[254:255]
	v_lshl_add_u64 v[250:251], v[30:31], 0, v[250:251]
	v_lshl_add_u64 v[252:253], v[250:251], 0, s[100:101]
	v_cvt_pk_bf16_f32 v240, v240, v241
	v_cvt_pk_bf16_f32 v241, v242, v243
	v_cvt_pk_bf16_f32 v244, v244, v245
	v_cvt_pk_bf16_f32 v245, v246, v247
	global_store_dwordx2 v[250:251], v[240:241], off offset:256
	global_store_dwordx2 v[252:253], v[244:245], off offset:256
	v_fmac_f32_e32 v20, v16, v16
	v_mul_f32_e32 v21, v19, v19
	v_cvt_pk_bf16_f32 v16, v16, v17
	v_cvt_pk_bf16_f32 v17, v18, v19
	v_lshlrev_b64 v[16:17], 11, v[86:87]
	v_mul_f32_e32 v25, v23, v23
	v_fmac_f32_e32 v21, v18, v18
	v_lshl_add_u64 v[16:17], v[16:17], 0, v[164:165]
	s_waitcnt vmcnt(27)
	v_pk_add_f32 v[14:15], v[14:15], v[78:79]
	v_pk_add_f32 v[12:13], v[12:13], v[76:77]
	v_fmac_f32_e32 v25, v22, v22
	v_add_f32_e32 v20, v20, v21
	v_lshl_add_u64 v[18:19], v[16:17], 2, s[26:27]
	v_mul_f32_e32 v21, v13, v13
	v_mul_f32_e32 v22, v15, v15
	v_mov_b32_e32 v240, v12
	v_mov_b32_e32 v241, v13
	v_mov_b32_e32 v242, v14
	v_mov_b32_e32 v243, v15
	v_fmac_f32_e32 v21, v12, v12
	v_fmac_f32_e32 v22, v14, v14
	v_cvt_pk_bf16_f32 v12, v12, v13
	v_cvt_pk_bf16_f32 v13, v14, v15
	v_lshl_add_u64 v[14:15], v[16:17], 1, s[10:11]
	s_waitcnt vmcnt(26)
	v_pk_add_f32 v[8:9], v[8:9], v[72:73]
	v_pk_add_f32 v[10:11], v[10:11], v[74:75]
	v_mul_f32_e32 v12, v9, v9
	v_mov_b32_e32 v244, v8
	v_mov_b32_e32 v245, v9
	v_mov_b32_e32 v246, v10
	v_mov_b32_e32 v247, v11
	v_mov_b32_dpp v244, v240 row_ror:8 row_mask:0xf bank_mask:0x3
	v_mov_b32_dpp v245, v241 row_ror:8 row_mask:0xf bank_mask:0x3
	v_mov_b32_dpp v246, v242 row_ror:8 row_mask:0xf bank_mask:0x3
	v_mov_b32_dpp v247, v243 row_ror:8 row_mask:0xf bank_mask:0x3
	v_mov_b32_dpp v240, v8 row_ror:8 row_mask:0xf bank_mask:0xc
	v_mov_b32_dpp v241, v9 row_ror:8 row_mask:0xf bank_mask:0xc
	v_mov_b32_dpp v242, v10 row_ror:8 row_mask:0xf bank_mask:0xc
	v_mov_b32_dpp v243, v11 row_ror:8 row_mask:0xf bank_mask:0xc
	v_lshl_add_u64 v[250:251], v[18:19], 0, v[254:255]
	v_lshl_add_u64 v[252:253], v[250:251], 0, s[98:99]
	global_store_dwordx4 v[250:251], v[240:243], off
	global_store_dwordx4 v[252:253], v[244:247], off
	v_ashrrev_i64 v[250:251], 1, v[254:255]
	v_lshl_add_u64 v[250:251], v[14:15], 0, v[250:251]
	v_lshl_add_u64 v[252:253], v[250:251], 0, s[100:101]
	v_cvt_pk_bf16_f32 v240, v240, v241
	v_cvt_pk_bf16_f32 v241, v242, v243
	v_cvt_pk_bf16_f32 v244, v244, v245
	v_cvt_pk_bf16_f32 v245, v246, v247
	global_store_dwordx2 v[250:251], v[240:241], off
	global_store_dwordx2 v[252:253], v[244:245], off
	v_fmac_f32_e32 v12, v8, v8
	v_mul_f32_e32 v13, v11, v11
	v_cvt_pk_bf16_f32 v8, v8, v9
	v_cvt_pk_bf16_f32 v9, v10, v11
	s_waitcnt vmcnt(28)
	v_pk_add_f32 v[6:7], v[6:7], v[70:71]
	v_pk_add_f32 v[4:5], v[4:5], v[68:69]
	v_fmac_f32_e32 v13, v10, v10
	v_mul_f32_e32 v8, v5, v5
	v_mul_f32_e32 v9, v7, v7
	v_add_f32_e32 v21, v21, v22
	v_add_f32_e32 v12, v12, v13
	v_fmac_f32_e32 v8, v4, v4
	v_fmac_f32_e32 v9, v6, v6
	v_mul_f32_e32 v45, v43, v43
	v_mul_f32_e32 v29, v27, v27
	v_add_f32_e32 v12, v21, v12
	v_add_f32_e32 v8, v8, v9
	v_fmac_f32_e32 v45, v42, v42
	v_fmac_f32_e32 v29, v26, v26
	v_add_f32_e32 v12, v12, v8
	s_waitcnt vmcnt(28)
	v_pk_add_f32 v[10:11], v[2:3], v[66:67]
	v_pk_add_f32 v[8:9], v[0:1], v[64:65]
	v_add_f32_e32 v44, v44, v45
	v_add_f32_e32 v37, v37, v38
	v_add_f32_e32 v28, v28, v29
	v_mul_f32_e32 v0, v9, v9
	v_mul_f32_e32 v1, v11, v11
	v_add_f32_e32 v44, v49, v44
	v_add_f32_e32 v40, v40, v41
	v_add_f32_e32 v28, v37, v28
	v_add_f32_e32 v24, v24, v25
	v_fmac_f32_e32 v0, v8, v8
	v_fmac_f32_e32 v1, v10, v10
	v_add_f32_e32 v40, v44, v40
	v_add_f32_e32 v24, v28, v24
	v_add_f32_e32 v0, v0, v1
	v_add_f32_e32 v36, v40, v36
	v_add_f32_e32 v20, v24, v20
	v_add_f32_e32 v3, v12, v0
	v_mov_b32_e32 v240, v4
	v_mov_b32_e32 v241, v5
	v_mov_b32_e32 v242, v6
	v_mov_b32_e32 v243, v7
	ds_bpermute_b32 v0, v90, v48
	ds_bpermute_b32 v1, v90, v36
	v_cvt_pk_bf16_f32 v4, v4, v5
	v_cvt_pk_bf16_f32 v5, v6, v7
	ds_bpermute_b32 v2, v90, v20
	ds_bpermute_b32 v6, v90, v3
	s_waitcnt lgkmcnt(3)
	v_add_f32_e32 v0, v48, v0
	s_waitcnt lgkmcnt(2)
	v_add_f32_e32 v1, v36, v1
	s_waitcnt lgkmcnt(1)
	v_add_f32_e32 v2, v20, v2
	s_waitcnt lgkmcnt(0)
	v_add_f32_e32 v4, v3, v6
	ds_bpermute_b32 v3, v91, v0
	ds_bpermute_b32 v5, v91, v1
	ds_bpermute_b32 v6, v91, v2
	ds_bpermute_b32 v7, v91, v4
	v_mov_b32_e32 v244, v8
	v_mov_b32_e32 v245, v9
	v_mov_b32_e32 v246, v10
	v_mov_b32_e32 v247, v11
	v_mov_b32_dpp v244, v240 row_ror:8 row_mask:0xf bank_mask:0x3
	v_mov_b32_dpp v245, v241 row_ror:8 row_mask:0xf bank_mask:0x3
	v_mov_b32_dpp v246, v242 row_ror:8 row_mask:0xf bank_mask:0x3
	v_mov_b32_dpp v247, v243 row_ror:8 row_mask:0xf bank_mask:0x3
	v_mov_b32_dpp v240, v8 row_ror:8 row_mask:0xf bank_mask:0xc
	v_mov_b32_dpp v241, v9 row_ror:8 row_mask:0xf bank_mask:0xc
	v_mov_b32_dpp v242, v10 row_ror:8 row_mask:0xf bank_mask:0xc
	v_mov_b32_dpp v243, v11 row_ror:8 row_mask:0xf bank_mask:0xc
	v_lshl_add_u64 v[250:251], v[18:19], 0, v[254:255]
	v_lshl_add_u64 v[252:253], v[250:251], 0, s[98:99]
	global_store_dwordx4 v[250:251], v[240:243], off offset:512
	global_store_dwordx4 v[252:253], v[244:247], off offset:512
	v_ashrrev_i64 v[250:251], 1, v[254:255]
	v_lshl_add_u64 v[250:251], v[14:15], 0, v[250:251]
	v_lshl_add_u64 v[252:253], v[250:251], 0, s[100:101]
	v_cvt_pk_bf16_f32 v240, v240, v241
	v_cvt_pk_bf16_f32 v241, v242, v243
	v_cvt_pk_bf16_f32 v244, v244, v245
	v_cvt_pk_bf16_f32 v245, v246, v247
	global_store_dwordx2 v[250:251], v[240:241], off offset:256
	global_store_dwordx2 v[252:253], v[244:245], off offset:256
	s_nop 1
	v_cvt_pk_bf16_f32 v8, v8, v9
	v_cvt_pk_bf16_f32 v9, v10, v11
	s_and_saveexec_b64 s[6:7], s[2:3]
	s_cbranch_execz .LBB0_526
	s_waitcnt lgkmcnt(3)
	v_add_f32_e32 v0, v0, v3
	s_waitcnt lgkmcnt(0)
	v_add_f32_e32 v4, v4, v7
	v_add_f32_e32 v2, v2, v6
	v_add_f32_e32 v1, v1, v5
	global_atomic_add_f32 v[84:85], v0, off offset:512
	global_atomic_add_f32 v[84:85], v1, off offset:576
	global_atomic_add_f32 v[84:85], v2, off offset:640
	global_atomic_add_f32 v[84:85], v4, off offset:704

.LBB0_995:
	s_mov_b32 s98, 0x10000
	s_mov_b32 s99, 0
	s_mov_b32 s100, 0x8000
	s_mov_b32 s101, 0
	v_bfe_u32 v255, v220, 3, 1
	v_sub_u32_e32 v255, 0, v255
	v_and_b32_e32 v254, 0xffff0040, v255
	v_lshl_add_u32 v168, s38, 8, v180
	v_lshl_or_b32 v164, s39, 8, v182
	v_readlane_b32 s72, v248, 0
	v_ashrrev_i32_e32 v165, 31, v164
	v_ashrrev_i32_e32 v169, 31, v168
	v_readlane_b32 s78, v248, 6
	v_readlane_b32 s79, v248, 7
	v_lshlrev_b64 v[128:129], 13, v[168:169]
	v_or_b32_e32 v174, 32, v168
	v_lshl_add_u64 v[166:167], v[164:165], 2, s[78:79]
	v_lshl_add_u64 v[234:235], v[166:167], 0, v[128:129]
	v_or_b32_e32 v128, 16, v168
	v_ashrrev_i32_e32 v129, 31, v128
	global_load_dwordx4 v[188:191], v[234:235], off
	global_load_dwordx4 v[192:195], v[234:235], off offset:64
	global_load_dwordx4 v[196:199], v[234:235], off offset:512
	global_load_dwordx4 v[200:203], v[234:235], off offset:576
	v_lshlrev_b64 v[130:131], 13, v[128:129]
	v_lshl_add_u64 v[176:177], v[166:167], 0, v[130:131]
	global_load_dwordx4 v[204:207], v[176:177], off
	global_load_dwordx4 v[208:211], v[176:177], off offset:64
	v_or_b32_e32 v170, 48, v168
	v_ashrrev_i32_e32 v175, 31, v174
	v_ashrrev_i32_e32 v171, 31, v170
	v_lshlrev_b64 v[130:131], 11, v[168:169]
	v_lshlrev_b64 v[132:133], 13, v[174:175]
	v_lshlrev_b64 v[134:135], 13, v[170:171]
	v_lshl_add_u64 v[130:131], v[130:131], 0, v[164:165]
	v_lshlrev_b64 v[128:129], 11, v[128:129]
	v_lshl_add_u64 v[178:179], v[166:167], 0, v[132:133]
	v_lshl_add_u64 v[172:173], v[166:167], 0, v[134:135]
	v_lshl_add_u64 v[236:237], v[130:131], 1, s[8:9]
	v_lshl_add_u64 v[238:239], v[128:129], 0, v[164:165]
	global_load_dwordx4 v[212:215], v[176:177], off offset:512
	global_load_dwordx4 v[216:219], v[176:177], off offset:576
	global_load_dwordx4 v[222:225], v[178:179], off
	global_load_dwordx4 v[226:229], v[178:179], off offset:64
	global_load_dwordx4 v[230:233], v[178:179], off offset:512
	global_load_dwordx4 v[144:147], v[178:179], off offset:576
	global_load_dwordx4 v[140:143], v[172:173], off
	global_load_dwordx4 v[136:139], v[172:173], off offset:64
	global_load_dwordx4 v[132:135], v[172:173], off offset:512
	global_load_dwordx4 v[128:131], v[172:173], off offset:576
	v_readlane_b32 s73, v248, 1
	v_readlane_b32 s74, v248, 2
	v_readlane_b32 s75, v248, 3
	v_readlane_b32 s76, v248, 4
	v_readlane_b32 s77, v248, 5
	s_waitcnt vmcnt(0)
	v_pk_add_f32 v[126:127], v[126:127], v[190:191]
	v_pk_add_f32 v[124:125], v[124:125], v[188:189]
	v_pk_add_f32 v[120:121], v[120:121], v[192:193]
	v_pk_add_f32 v[122:123], v[122:123], v[194:195]
	v_pk_add_f32 v[112:113], v[112:113], v[196:197]
	v_mov_b32_e32 v240, v124
	v_mov_b32_e32 v241, v125
	v_mov_b32_e32 v242, v126
	v_mov_b32_e32 v243, v127
	v_mul_f32_e32 v187, v125, v125
	v_cvt_pk_bf16_f32 v188, v124, v125
	v_cvt_pk_bf16_f32 v189, v126, v127
	v_pk_add_f32 v[114:115], v[114:115], v[198:199]
	v_mul_f32_e32 v125, v121, v121
	v_pk_add_f32 v[108:109], v[108:109], v[200:201]
	v_mul_f32_e32 v190, v127, v127
	v_mul_f32_e32 v127, v123, v123
	v_mul_f32_e32 v191, v113, v113
	v_mov_b32_e32 v244, v120
	v_mov_b32_e32 v245, v121
	v_mov_b32_e32 v246, v122
	v_mov_b32_e32 v247, v123
	v_mov_b32_dpp v244, v240 row_ror:8 row_mask:0xf bank_mask:0x3
	v_mov_b32_dpp v245, v241 row_ror:8 row_mask:0xf bank_mask:0x3
	v_mov_b32_dpp v246, v242 row_ror:8 row_mask:0xf bank_mask:0x3
	v_mov_b32_dpp v247, v243 row_ror:8 row_mask:0xf bank_mask:0x3
	v_mov_b32_dpp v240, v120 row_ror:8 row_mask:0xf bank_mask:0xc
	v_mov_b32_dpp v241, v121 row_ror:8 row_mask:0xf bank_mask:0xc
	v_mov_b32_dpp v242, v122 row_ror:8 row_mask:0xf bank_mask:0xc
	v_mov_b32_dpp v243, v123 row_ror:8 row_mask:0xf bank_mask:0xc
	v_lshl_add_u64 v[250:251], v[234:235], 0, v[254:255]
	v_lshl_add_u64 v[252:253], v[250:251], 0, s[98:99]
	global_store_dwordx4 v[250:251], v[240:243], off
	global_store_dwordx4 v[252:253], v[244:247], off
	v_ashrrev_i64 v[250:251], 1, v[254:255]
	v_lshl_add_u64 v[250:251], v[236:237], 0, v[250:251]
	v_lshl_add_u64 v[252:253], v[250:251], 0, s[100:101]
	v_cvt_pk_bf16_f32 v240, v240, v241
	v_cvt_pk_bf16_f32 v241, v242, v243
	v_cvt_pk_bf16_f32 v244, v244, v245
	v_cvt_pk_bf16_f32 v245, v246, v247
	global_store_dwordx2 v[250:251], v[240:241], off
	global_store_dwordx2 v[252:253], v[244:245], off
	v_fmac_f32_e32 v125, v120, v120
	v_pk_add_f32 v[110:111], v[110:111], v[202:203]
	v_cvt_pk_bf16_f32 v120, v120, v121
	v_cvt_pk_bf16_f32 v121, v122, v123
	v_mul_f32_e32 v192, v115, v115
	v_mul_f32_e32 v193, v109, v109
	v_fmac_f32_e32 v187, v124, v124
	v_fmac_f32_e32 v190, v126, v126
	v_fmac_f32_e32 v127, v122, v122
	v_fmac_f32_e32 v191, v112, v112
	v_mov_b32_e32 v240, v112
	v_mov_b32_e32 v241, v113
	v_mov_b32_e32 v242, v114
	v_mov_b32_e32 v243, v115
	v_mul_f32_e32 v194, v111, v111
	v_pk_add_f32 v[118:119], v[118:119], v[206:207]
	v_cvt_pk_bf16_f32 v112, v112, v113
	v_cvt_pk_bf16_f32 v113, v114, v115
	v_pk_add_f32 v[116:117], v[116:117], v[204:205]
	v_fmac_f32_e32 v192, v114, v114
	v_fmac_f32_e32 v193, v108, v108
	v_add_f32_e32 v123, v187, v190
	v_add_f32_e32 v124, v125, v127
	v_mov_b32_e32 v244, v108
	v_mov_b32_e32 v245, v109
	v_mov_b32_e32 v246, v110
	v_mov_b32_e32 v247, v111
	v_mov_b32_dpp v244, v240 row_ror:8 row_mask:0xf bank_mask:0x3
	v_mov_b32_dpp v245, v241 row_ror:8 row_mask:0xf bank_mask:0x3
	v_mov_b32_dpp v246, v242 row_ror:8 row_mask:0xf bank_mask:0x3
	v_mov_b32_dpp v247, v243 row_ror:8 row_mask:0xf bank_mask:0x3
	v_mov_b32_dpp v240, v108 row_ror:8 row_mask:0xf bank_mask:0xc
	v_mov_b32_dpp v241, v109 row_ror:8 row_mask:0xf bank_mask:0xc
	v_mov_b32_dpp v242, v110 row_ror:8 row_mask:0xf bank_mask:0xc
	v_mov_b32_dpp v243, v111 row_ror:8 row_mask:0xf bank_mask:0xc
	v_lshl_add_u64 v[250:251], v[234:235], 0, v[254:255]
	v_lshl_add_u64 v[252:253], v[250:251], 0, s[98:99]
	global_store_dwordx4 v[250:251], v[240:243], off offset:512
	global_store_dwordx4 v[252:253], v[244:247], off offset:512
	v_ashrrev_i64 v[250:251], 1, v[254:255]
	v_lshl_add_u64 v[250:251], v[236:237], 0, v[250:251]
	v_lshl_add_u64 v[252:253], v[250:251], 0, s[100:101]
	v_cvt_pk_bf16_f32 v240, v240, v241
	v_cvt_pk_bf16_f32 v241, v242, v243
	v_cvt_pk_bf16_f32 v244, v244, v245
	v_cvt_pk_bf16_f32 v245, v246, v247
	global_store_dwordx2 v[250:251], v[240:241], off offset:256
	global_store_dwordx2 v[252:253], v[244:245], off offset:256
	v_fmac_f32_e32 v194, v110, v110
	v_mul_f32_e32 v122, v117, v117
	v_cvt_pk_bf16_f32 v108, v108, v109
	v_cvt_pk_bf16_f32 v109, v110, v111
	v_add_f32_e32 v120, v191, v192
	v_add_f32_e32 v115, v123, v124
	v_mov_b32_e32 v240, v116
	v_mov_b32_e32 v241, v117
	v_mov_b32_e32 v242, v118
	v_mov_b32_e32 v243, v119
	v_mul_f32_e32 v108, v119, v119
	v_add_f32_e32 v114, v193, v194
	v_add_f32_e32 v110, v115, v120
	v_fmac_f32_e32 v122, v116, v116
	v_fmac_f32_e32 v108, v118, v118
	v_add_f32_e32 v112, v110, v114
	v_add_f32_e32 v113, v122, v108
	v_cvt_pk_bf16_f32 v108, v116, v117
	v_lshl_add_u64 v[110:111], v[238:239], 1, s[8:9]
	v_pk_add_f32 v[104:105], v[104:105], v[208:209]
	v_cvt_pk_bf16_f32 v109, v118, v119
	v_pk_add_f32 v[106:107], v[106:107], v[210:211]
	v_mul_f32_e32 v108, v105, v105
	v_mov_b32_e32 v244, v104
	v_mov_b32_e32 v245, v105
	v_mov_b32_e32 v246, v106
	v_mov_b32_e32 v247, v107
	v_mov_b32_dpp v244, v240 row_ror:8 row_mask:0xf bank_mask:0x3
	v_mov_b32_dpp v245, v241 row_ror:8 row_mask:0xf bank_mask:0x3
	v_mov_b32_dpp v246, v242 row_ror:8 row_mask:0xf bank_mask:0x3
	v_mov_b32_dpp v247, v243 row_ror:8 row_mask:0xf bank_mask:0x3
	v_mov_b32_dpp v240, v104 row_ror:8 row_mask:0xf bank_mask:0xc
	v_mov_b32_dpp v241, v105 row_ror:8 row_mask:0xf bank_mask:0xc
	v_mov_b32_dpp v242, v106 row_ror:8 row_mask:0xf bank_mask:0xc
	v_mov_b32_dpp v243, v107 row_ror:8 row_mask:0xf bank_mask:0xc
	v_lshl_add_u64 v[250:251], v[176:177], 0, v[254:255]
	v_lshl_add_u64 v[252:253], v[250:251], 0, s[98:99]
	global_store_dwordx4 v[250:251], v[240:243], off
	global_store_dwordx4 v[252:253], v[244:247], off
	v_ashrrev_i64 v[250:251], 1, v[254:255]
	v_lshl_add_u64 v[250:251], v[110:111], 0, v[250:251]
	v_lshl_add_u64 v[252:253], v[250:251], 0, s[100:101]
	v_cvt_pk_bf16_f32 v240, v240, v241
	v_cvt_pk_bf16_f32 v241, v242, v243
	v_cvt_pk_bf16_f32 v244, v244, v245
	v_cvt_pk_bf16_f32 v245, v246, v247
	global_store_dwordx2 v[250:251], v[240:241], off
	global_store_dwordx2 v[252:253], v[244:245], off
	v_fmac_f32_e32 v108, v104, v104
	v_pk_add_f32 v[100:101], v[100:101], v[212:213]
	v_cvt_pk_bf16_f32 v104, v104, v105
	v_cvt_pk_bf16_f32 v105, v106, v107
	v_pk_add_f32 v[102:103], v[102:103], v[214:215]
	v_mul_f32_e32 v104, v101, v101
	v_mov_b32_e32 v240, v100
	v_mov_b32_e32 v241, v101
	v_mov_b32_e32 v242, v102
	v_mov_b32_e32 v243, v103
	v_fmac_f32_e32 v104, v100, v100
	v_pk_add_f32 v[96:97], v[96:97], v[216:217]
	v_cvt_pk_bf16_f32 v100, v100, v101
	v_cvt_pk_bf16_f32 v101, v102, v103
	v_pk_add_f32 v[98:99], v[98:99], v[218:219]
	v_mul_f32_e32 v100, v97, v97
	v_mov_b32_e32 v244, v96
	v_mov_b32_e32 v245, v97
	v_mov_b32_e32 v246, v98
	v_mov_b32_e32 v247, v99
	v_mov_b32_dpp v244, v240 row_ror:8 row_mask:0xf bank_mask:0x3
	v_mov_b32_dpp v245, v241 row_ror:8 row_mask:0xf bank_mask:0x3
	v_mov_b32_dpp v246, v242 row_ror:8 row_mask:0xf bank_mask:0x3
	v_mov_b32_dpp v247, v243 row_ror:8 row_mask:0xf bank_mask:0x3
	v_mov_b32_dpp v240, v96 row_ror:8 row_mask:0xf bank_mask:0xc
	v_mov_b32_dpp v241, v97 row_ror:8 row_mask:0xf bank_mask:0xc
	v_mov_b32_dpp v242, v98 row_ror:8 row_mask:0xf bank_mask:0xc
	v_mov_b32_dpp v243, v99 row_ror:8 row_mask:0xf bank_mask:0xc
	v_lshl_add_u64 v[250:251], v[176:177], 0, v[254:255]
	v_lshl_add_u64 v[252:253], v[250:251], 0, s[98:99]
	global_store_dwordx4 v[250:251], v[240:243], off offset:512
	global_store_dwordx4 v[252:253], v[244:247], off offset:512
	v_ashrrev_i64 v[250:251], 1, v[254:255]
	v_lshl_add_u64 v[250:251], v[110:111], 0, v[250:251]
	v_lshl_add_u64 v[252:253], v[250:251], 0, s[100:101]
	v_cvt_pk_bf16_f32 v240, v240, v241
	v_cvt_pk_bf16_f32 v241, v242, v243
	v_cvt_pk_bf16_f32 v244, v244, v245
	v_cvt_pk_bf16_f32 v245, v246, v247
	global_store_dwordx2 v[250:251], v[240:241], off offset:256
	global_store_dwordx2 v[252:253], v[244:245], off offset:256
	v_fmac_f32_e32 v100, v96, v96
	v_mul_f32_e32 v101, v99, v99
	v_cvt_pk_bf16_f32 v96, v96, v97
	v_cvt_pk_bf16_f32 v97, v98, v99
	v_lshlrev_b64 v[96:97], 11, v[174:175]
	v_pk_add_f32 v[94:95], v[94:95], v[224:225]
	v_pk_add_f32 v[92:93], v[92:93], v[222:223]
	v_fmac_f32_e32 v101, v98, v98
	v_lshl_add_u64 v[96:97], v[96:97], 0, v[164:165]
	v_mul_f32_e32 v98, v93, v93
	v_mul_f32_e32 v99, v95, v95
	v_mov_b32_e32 v240, v92
	v_mov_b32_e32 v241, v93
	v_mov_b32_e32 v242, v94
	v_mov_b32_e32 v243, v95
	v_fmac_f32_e32 v98, v92, v92
	v_fmac_f32_e32 v99, v94, v94
	v_cvt_pk_bf16_f32 v92, v92, v93
	v_cvt_pk_bf16_f32 v93, v94, v95
	v_lshl_add_u64 v[94:95], v[96:97], 1, s[8:9]
	v_pk_add_f32 v[88:89], v[88:89], v[226:227]
	v_pk_add_f32 v[90:91], v[90:91], v[228:229]
	v_mul_f32_e32 v92, v89, v89
	v_mov_b32_e32 v244, v88
	v_mov_b32_e32 v245, v89
	v_mov_b32_e32 v246, v90
	v_mov_b32_e32 v247, v91
	v_mov_b32_dpp v244, v240 row_ror:8 row_mask:0xf bank_mask:0x3
	v_mov_b32_dpp v245, v241 row_ror:8 row_mask:0xf bank_mask:0x3
	v_mov_b32_dpp v246, v242 row_ror:8 row_mask:0xf bank_mask:0x3
	v_mov_b32_dpp v247, v243 row_ror:8 row_mask:0xf bank_mask:0x3
	v_mov_b32_dpp v240, v88 row_ror:8 row_mask:0xf bank_mask:0xc
	v_mov_b32_dpp v241, v89 row_ror:8 row_mask:0xf bank_mask:0xc
	v_mov_b32_dpp v242, v90 row_ror:8 row_mask:0xf bank_mask:0xc
	v_mov_b32_dpp v243, v91 row_ror:8 row_mask:0xf bank_mask:0xc
	v_lshl_add_u64 v[250:251], v[178:179], 0, v[254:255]
	v_lshl_add_u64 v[252:253], v[250:251], 0, s[98:99]
	global_store_dwordx4 v[250:251], v[240:243], off
	global_store_dwordx4 v[252:253], v[244:247], off
	v_ashrrev_i64 v[250:251], 1, v[254:255]
	v_lshl_add_u64 v[250:251], v[94:95], 0, v[250:251]
	v_lshl_add_u64 v[252:253], v[250:251], 0, s[100:101]
	v_cvt_pk_bf16_f32 v240, v240, v241
	v_cvt_pk_bf16_f32 v241, v242, v243
	v_cvt_pk_bf16_f32 v244, v244, v245
	v_cvt_pk_bf16_f32 v245, v246, v247
	global_store_dwordx2 v[250:251], v[240:241], off
	global_store_dwordx2 v[252:253], v[244:245], off
	v_fmac_f32_e32 v92, v88, v88
	v_pk_add_f32 v[84:85], v[84:85], v[230:231]
	v_cvt_pk_bf16_f32 v88, v88, v89
	v_cvt_pk_bf16_f32 v89, v90, v91
	v_pk_add_f32 v[86:87], v[86:87], v[232:233]
	v_mul_f32_e32 v88, v85, v85
	v_mov_b32_e32 v240, v84
	v_mov_b32_e32 v241, v85
	v_mov_b32_e32 v242, v86
	v_mov_b32_e32 v243, v87
	v_fmac_f32_e32 v88, v84, v84
	v_pk_add_f32 v[80:81], v[80:81], v[144:145]
	v_cvt_pk_bf16_f32 v84, v84, v85
	v_cvt_pk_bf16_f32 v85, v86, v87
	v_pk_add_f32 v[82:83], v[82:83], v[146:147]
	v_mul_f32_e32 v84, v81, v81
	v_mov_b32_e32 v244, v80
	v_mov_b32_e32 v245, v81
	v_mov_b32_e32 v246, v82
	v_mov_b32_e32 v247, v83
	v_mov_b32_dpp v244, v240 row_ror:8 row_mask:0xf bank_mask:0x3
	v_mov_b32_dpp v245, v241 row_ror:8 row_mask:0xf bank_mask:0x3
	v_mov_b32_dpp v246, v242 row_ror:8 row_mask:0xf bank_mask:0x3
	v_mov_b32_dpp v247, v243 row_ror:8 row_mask:0xf bank_mask:0x3
	v_mov_b32_dpp v240, v80 row_ror:8 row_mask:0xf bank_mask:0xc
	v_mov_b32_dpp v241, v81 row_ror:8 row_mask:0xf bank_mask:0xc
	v_mov_b32_dpp v242, v82 row_ror:8 row_mask:0xf bank_mask:0xc
	v_mov_b32_dpp v243, v83 row_ror:8 row_mask:0xf bank_mask:0xc
	v_lshl_add_u64 v[250:251], v[178:179], 0, v[254:255]
	v_lshl_add_u64 v[252:253], v[250:251], 0, s[98:99]
	global_store_dwordx4 v[250:251], v[240:243], off offset:512
	global_store_dwordx4 v[252:253], v[244:247], off offset:512
	v_ashrrev_i64 v[250:251], 1, v[254:255]
	v_lshl_add_u64 v[250:251], v[94:95], 0, v[250:251]
	v_lshl_add_u64 v[252:253], v[250:251], 0, s[100:101]
	v_cvt_pk_bf16_f32 v240, v240, v241
	v_cvt_pk_bf16_f32 v241, v242, v243
	v_cvt_pk_bf16_f32 v244, v244, v245
	v_cvt_pk_bf16_f32 v245, v246, v247
	global_store_dwordx2 v[250:251], v[240:241], off offset:256
	global_store_dwordx2 v[252:253], v[244:245], off offset:256
	v_fmac_f32_e32 v84, v80, v80
	v_mul_f32_e32 v85, v83, v83
	v_cvt_pk_bf16_f32 v80, v80, v81
	v_cvt_pk_bf16_f32 v81, v82, v83
	v_lshlrev_b64 v[80:81], 11, v[170:171]
	v_pk_add_f32 v[78:79], v[78:79], v[142:143]
	v_pk_add_f32 v[76:77], v[76:77], v[140:141]
	v_fmac_f32_e32 v85, v82, v82
	v_lshl_add_u64 v[80:81], v[80:81], 0, v[164:165]
	v_mul_f32_e32 v82, v77, v77
	v_mul_f32_e32 v83, v79, v79
	v_mov_b32_e32 v240, v76
	v_mov_b32_e32 v241, v77
	v_mov_b32_e32 v242, v78
	v_mov_b32_e32 v243, v79
	v_fmac_f32_e32 v82, v76, v76
	v_fmac_f32_e32 v83, v78, v78
	v_cvt_pk_bf16_f32 v76, v76, v77
	v_cvt_pk_bf16_f32 v77, v78, v79
	v_lshl_add_u64 v[78:79], v[80:81], 1, s[8:9]
	v_pk_add_f32 v[72:73], v[72:73], v[136:137]
	v_pk_add_f32 v[74:75], v[74:75], v[138:139]
	v_mul_f32_e32 v76, v73, v73
	v_mov_b32_e32 v244, v72
	v_mov_b32_e32 v245, v73
	v_mov_b32_e32 v246, v74
	v_mov_b32_e32 v247, v75
	v_mov_b32_dpp v244, v240 row_ror:8 row_mask:0xf bank_mask:0x3
	v_mov_b32_dpp v245, v241 row_ror:8 row_mask:0xf bank_mask:0x3
	v_mov_b32_dpp v246, v242 row_ror:8 row_mask:0xf bank_mask:0x3
	v_mov_b32_dpp v247, v243 row_ror:8 row_mask:0xf bank_mask:0x3
	v_mov_b32_dpp v240, v72 row_ror:8 row_mask:0xf bank_mask:0xc
	v_mov_b32_dpp v241, v73 row_ror:8 row_mask:0xf bank_mask:0xc
	v_mov_b32_dpp v242, v74 row_ror:8 row_mask:0xf bank_mask:0xc
	v_mov_b32_dpp v243, v75 row_ror:8 row_mask:0xf bank_mask:0xc
	v_lshl_add_u64 v[250:251], v[172:173], 0, v[254:255]
	v_lshl_add_u64 v[252:253], v[250:251], 0, s[98:99]
	global_store_dwordx4 v[250:251], v[240:243], off
	global_store_dwordx4 v[252:253], v[244:247], off
	v_ashrrev_i64 v[250:251], 1, v[254:255]
	v_lshl_add_u64 v[250:251], v[78:79], 0, v[250:251]
	v_lshl_add_u64 v[252:253], v[250:251], 0, s[100:101]
	v_cvt_pk_bf16_f32 v240, v240, v241
	v_cvt_pk_bf16_f32 v241, v242, v243
	v_cvt_pk_bf16_f32 v244, v244, v245
	v_cvt_pk_bf16_f32 v245, v246, v247
	global_store_dwordx2 v[250:251], v[240:241], off
	global_store_dwordx2 v[252:253], v[244:245], off
	v_fmac_f32_e32 v76, v72, v72
	v_mul_f32_e32 v77, v75, v75
	v_cvt_pk_bf16_f32 v72, v72, v73
	v_cvt_pk_bf16_f32 v73, v74, v75
	v_pk_add_f32 v[70:71], v[70:71], v[134:135]
	v_pk_add_f32 v[68:69], v[68:69], v[132:133]
	v_fmac_f32_e32 v77, v74, v74
	v_mul_f32_e32 v72, v69, v69
	v_mul_f32_e32 v73, v71, v71
	v_add_f32_e32 v82, v82, v83
	v_add_f32_e32 v76, v76, v77
	v_fmac_f32_e32 v72, v68, v68
	v_fmac_f32_e32 v73, v70, v70
	v_add_f32_e32 v76, v82, v76
	v_add_f32_e32 v72, v72, v73
	v_add_f32_e32 v76, v76, v72
	v_pk_add_f32 v[74:75], v[66:67], v[130:131]
	v_pk_add_f32 v[72:73], v[64:65], v[128:129]
	v_mul_f32_e32 v65, v75, v75
	v_mul_f32_e32 v64, v73, v73
	v_fmac_f32_e32 v64, v72, v72
	v_fmac_f32_e32 v65, v74, v74
	v_mov_b32_e32 v240, v68
	v_mov_b32_e32 v241, v69
	v_mov_b32_e32 v242, v70
	v_mov_b32_e32 v243, v71
	v_add_f32_e32 v64, v64, v65
	v_and_b32_e32 v65, 64, v186
	v_cvt_pk_bf16_f32 v68, v68, v69
	v_cvt_pk_bf16_f32 v69, v70, v71
	v_add_f32_e32 v67, v76, v64
	v_xor_b32_e32 v64, 16, v186
	v_add_u32_e32 v68, 64, v65
	v_mul_f32_e32 v109, v107, v107
	v_mul_f32_e32 v93, v91, v91
	v_cmp_lt_i32_e32 vcc, v64, v68
	v_fmac_f32_e32 v109, v106, v106
	v_mul_f32_e32 v105, v103, v103
	v_fmac_f32_e32 v93, v90, v90
	v_mul_f32_e32 v89, v87, v87
	v_cndmask_b32_e32 v64, v186, v64, vcc
	v_add_f32_e32 v108, v108, v109
	v_fmac_f32_e32 v105, v102, v102
	v_add_f32_e32 v98, v98, v99
	v_add_f32_e32 v92, v92, v93
	v_fmac_f32_e32 v89, v86, v86
	v_lshlrev_b32_e32 v96, 2, v64
	v_add_f32_e32 v108, v113, v108
	v_add_f32_e32 v104, v104, v105
	v_add_f32_e32 v92, v98, v92
	v_add_f32_e32 v88, v88, v89
	ds_bpermute_b32 v69, v96, v67
	v_add_f32_e32 v104, v108, v104
	v_add_f32_e32 v100, v100, v101
	v_add_f32_e32 v88, v92, v88
	v_add_f32_e32 v84, v84, v85
	v_add_f32_e32 v100, v104, v100
	v_add_f32_e32 v84, v88, v84
	ds_bpermute_b32 v64, v96, v112
	ds_bpermute_b32 v65, v96, v100
	ds_bpermute_b32 v66, v96, v84
	s_waitcnt lgkmcnt(3)
	v_add_f32_e32 v67, v67, v69
	v_xor_b32_e32 v69, 32, v186
	v_cmp_lt_i32_e32 vcc, v69, v68
	s_waitcnt lgkmcnt(2)
	v_add_f32_e32 v64, v112, v64
	s_waitcnt lgkmcnt(1)
	v_add_f32_e32 v65, v100, v65
	v_cndmask_b32_e32 v68, v186, v69, vcc
	s_waitcnt lgkmcnt(0)
	v_add_f32_e32 v66, v84, v66
	v_lshlrev_b32_e32 v97, 2, v68
	ds_bpermute_b32 v68, v97, v64
	ds_bpermute_b32 v69, v97, v65
	ds_bpermute_b32 v70, v97, v66
	ds_bpermute_b32 v71, v97, v67
	v_lshl_add_u64 v[84:85], v[168:169], 2, s[10:11]
	v_mov_b32_e32 v244, v72
	v_mov_b32_e32 v245, v73
	v_mov_b32_e32 v246, v74
	v_mov_b32_e32 v247, v75
	v_mov_b32_dpp v244, v240 row_ror:8 row_mask:0xf bank_mask:0x3
	v_mov_b32_dpp v245, v241 row_ror:8 row_mask:0xf bank_mask:0x3
	v_mov_b32_dpp v246, v242 row_ror:8 row_mask:0xf bank_mask:0x3
	v_mov_b32_dpp v247, v243 row_ror:8 row_mask:0xf bank_mask:0x3
	v_mov_b32_dpp v240, v72 row_ror:8 row_mask:0xf bank_mask:0xc
	v_mov_b32_dpp v241, v73 row_ror:8 row_mask:0xf bank_mask:0xc
	v_mov_b32_dpp v242, v74 row_ror:8 row_mask:0xf bank_mask:0xc
	v_mov_b32_dpp v243, v75 row_ror:8 row_mask:0xf bank_mask:0xc
	v_lshl_add_u64 v[250:251], v[172:173], 0, v[254:255]
	v_lshl_add_u64 v[252:253], v[250:251], 0, s[98:99]
	global_store_dwordx4 v[250:251], v[240:243], off offset:512
	global_store_dwordx4 v[252:253], v[244:247], off offset:512
	v_ashrrev_i64 v[250:251], 1, v[254:255]
	v_lshl_add_u64 v[250:251], v[78:79], 0, v[250:251]
	v_lshl_add_u64 v[252:253], v[250:251], 0, s[100:101]
	v_cvt_pk_bf16_f32 v240, v240, v241
	v_cvt_pk_bf16_f32 v241, v242, v243
	v_cvt_pk_bf16_f32 v244, v244, v245
	v_cvt_pk_bf16_f32 v245, v246, v247
	global_store_dwordx2 v[250:251], v[240:241], off offset:256
	global_store_dwordx2 v[252:253], v[244:245], off offset:256
	s_nop 1
	v_cvt_pk_bf16_f32 v72, v72, v73
	v_cvt_pk_bf16_f32 v73, v74, v75
	s_and_saveexec_b64 s[38:39], s[2:3]
	s_cbranch_execz .LBB0_997
	s_waitcnt lgkmcnt(3)
	v_add_f32_e32 v64, v64, v68
	s_waitcnt lgkmcnt(0)
	v_add_f32_e32 v67, v67, v71
	v_add_f32_e32 v66, v66, v70
	v_add_f32_e32 v65, v65, v69
	global_atomic_add_f32 v[84:85], v64, off
	global_atomic_add_f32 v[84:85], v65, off offset:64
	global_atomic_add_f32 v[84:85], v66, off offset:128
	global_atomic_add_f32 v[84:85], v67, off offset:192
.LBB0_997:
	s_or_b64 exec, exec, s[38:39]
	v_add_u32_e32 v64, 0x80, v168
	v_ashrrev_i32_e32 v65, 31, v64
	v_lshlrev_b64 v[66:67], 13, v[64:65]
	v_lshl_add_u64 v[142:143], v[166:167], 0, v[66:67]
	global_load_dwordx4 v[98:101], v[142:143], off
	global_load_dwordx4 v[102:105], v[142:143], off offset:64
	global_load_dwordx4 v[106:109], v[142:143], off offset:512
	global_load_dwordx4 v[110:113], v[142:143], off offset:576
	v_add_u32_e32 v66, 0x90, v168
	v_ashrrev_i32_e32 v67, 31, v66
	s_waitcnt lgkmcnt(2)
	v_lshlrev_b64 v[68:69], 13, v[66:67]
	v_lshl_add_u64 v[92:93], v[166:167], 0, v[68:69]
	global_load_dwordx4 v[114:117], v[92:93], off
	global_load_dwordx4 v[118:121], v[92:93], off offset:64
	v_add_u32_e32 v90, 0xa0, v168
	v_add_u32_e32 v88, 0xb0, v168
	v_ashrrev_i32_e32 v91, 31, v90
	v_ashrrev_i32_e32 v89, 31, v88
	v_lshlrev_b64 v[68:69], 13, v[90:91]
	s_waitcnt lgkmcnt(0)
	v_lshlrev_b64 v[70:71], 13, v[88:89]
	v_lshlrev_b64 v[64:65], 11, v[64:65]
	v_lshlrev_b64 v[66:67], 11, v[66:67]
	v_lshl_add_u64 v[94:95], v[166:167], 0, v[68:69]
	v_lshl_add_u64 v[86:87], v[166:167], 0, v[70:71]
	v_lshl_add_u64 v[144:145], v[64:65], 0, v[164:165]
	v_lshl_add_u64 v[146:147], v[66:67], 0, v[164:165]
	global_load_dwordx4 v[122:125], v[92:93], off offset:512
	global_load_dwordx4 v[126:129], v[92:93], off offset:576
	global_load_dwordx4 v[130:133], v[94:95], off
	global_load_dwordx4 v[134:137], v[94:95], off offset:64
	global_load_dwordx4 v[138:141], v[94:95], off offset:512
	global_load_dwordx4 v[80:83], v[94:95], off offset:576
	global_load_dwordx4 v[76:79], v[86:87], off
	global_load_dwordx4 v[72:75], v[86:87], off offset:64
	global_load_dwordx4 v[68:71], v[86:87], off offset:512
	global_load_dwordx4 v[64:67], v[86:87], off offset:576
	v_lshl_add_u64 v[144:145], v[144:145], 1, s[8:9]
	s_waitcnt vmcnt(15)
	v_pk_add_f32 v[62:63], v[62:63], v[100:101]
	v_pk_add_f32 v[60:61], v[60:61], v[98:99]
	s_waitcnt vmcnt(14)
	v_pk_add_f32 v[58:59], v[58:59], v[104:105]
	v_pk_add_f32 v[56:57], v[56:57], v[102:103]
	s_waitcnt vmcnt(13)
	v_pk_add_f32 v[50:51], v[50:51], v[108:109]
	v_pk_add_f32 v[48:49], v[48:49], v[106:107]
	v_mov_b32_e32 v240, v60
	v_mov_b32_e32 v241, v61
	v_mov_b32_e32 v242, v62
	v_mov_b32_e32 v243, v63
	v_mul_f32_e32 v100, v61, v61
	v_mul_f32_e32 v101, v63, v63
	v_cvt_pk_bf16_f32 v98, v60, v61
	v_cvt_pk_bf16_f32 v99, v62, v63
	v_mul_f32_e32 v61, v57, v57
	v_mul_f32_e32 v63, v59, v59
	s_waitcnt vmcnt(12)
	v_pk_add_f32 v[46:47], v[46:47], v[112:113]
	v_pk_add_f32 v[44:45], v[44:45], v[110:111]
	v_mul_f32_e32 v102, v49, v49
	v_mul_f32_e32 v103, v51, v51
	v_fmac_f32_e32 v100, v60, v60
	v_fmac_f32_e32 v101, v62, v62
	v_fmac_f32_e32 v61, v56, v56
	v_fmac_f32_e32 v63, v58, v58
	v_mul_f32_e32 v104, v45, v45
	v_mul_f32_e32 v105, v47, v47
	v_mov_b32_e32 v244, v56
	v_mov_b32_e32 v245, v57
	v_mov_b32_e32 v246, v58
	v_mov_b32_e32 v247, v59
	v_mov_b32_dpp v244, v240 row_ror:8 row_mask:0xf bank_mask:0x3
	v_mov_b32_dpp v245, v241 row_ror:8 row_mask:0xf bank_mask:0x3
	v_mov_b32_dpp v246, v242 row_ror:8 row_mask:0xf bank_mask:0x3
	v_mov_b32_dpp v247, v243 row_ror:8 row_mask:0xf bank_mask:0x3
	v_mov_b32_dpp v240, v56 row_ror:8 row_mask:0xf bank_mask:0xc
	v_mov_b32_dpp v241, v57 row_ror:8 row_mask:0xf bank_mask:0xc
	v_mov_b32_dpp v242, v58 row_ror:8 row_mask:0xf bank_mask:0xc
	v_mov_b32_dpp v243, v59 row_ror:8 row_mask:0xf bank_mask:0xc
	v_lshl_add_u64 v[250:251], v[142:143], 0, v[254:255]
	v_lshl_add_u64 v[252:253], v[250:251], 0, s[98:99]
	global_store_dwordx4 v[250:251], v[240:243], off
	global_store_dwordx4 v[252:253], v[244:247], off
	v_ashrrev_i64 v[250:251], 1, v[254:255]
	v_lshl_add_u64 v[250:251], v[144:145], 0, v[250:251]
	v_lshl_add_u64 v[252:253], v[250:251], 0, s[100:101]
	v_cvt_pk_bf16_f32 v240, v240, v241
	v_cvt_pk_bf16_f32 v241, v242, v243
	v_cvt_pk_bf16_f32 v244, v244, v245
	v_cvt_pk_bf16_f32 v245, v246, v247
	global_store_dwordx2 v[250:251], v[240:241], off
	global_store_dwordx2 v[252:253], v[244:245], off
	v_fmac_f32_e32 v102, v48, v48
	v_fmac_f32_e32 v103, v50, v50
	v_cvt_pk_bf16_f32 v56, v56, v57
	v_cvt_pk_bf16_f32 v57, v58, v59
	v_add_f32_e32 v58, v100, v101
	v_add_f32_e32 v59, v61, v63
	v_fmac_f32_e32 v104, v44, v44
	v_fmac_f32_e32 v105, v46, v46
	v_mov_b32_e32 v240, v48
	v_mov_b32_e32 v241, v49
	v_mov_b32_e32 v242, v50
	v_mov_b32_e32 v243, v51
	v_add_f32_e32 v56, v102, v103
	s_waitcnt vmcnt(15)
	v_pk_add_f32 v[54:55], v[54:55], v[116:117]
	v_cvt_pk_bf16_f32 v48, v48, v49
	v_cvt_pk_bf16_f32 v49, v50, v51
	v_add_f32_e32 v51, v58, v59
	v_add_f32_e32 v50, v104, v105
	v_mov_b32_e32 v244, v44
	v_mov_b32_e32 v245, v45
	v_mov_b32_e32 v246, v46
	v_mov_b32_e32 v247, v47
	v_mov_b32_dpp v244, v240 row_ror:8 row_mask:0xf bank_mask:0x3
	v_mov_b32_dpp v245, v241 row_ror:8 row_mask:0xf bank_mask:0x3
	v_mov_b32_dpp v246, v242 row_ror:8 row_mask:0xf bank_mask:0x3
	v_mov_b32_dpp v247, v243 row_ror:8 row_mask:0xf bank_mask:0x3
	v_mov_b32_dpp v240, v44 row_ror:8 row_mask:0xf bank_mask:0xc
	v_mov_b32_dpp v241, v45 row_ror:8 row_mask:0xf bank_mask:0xc
	v_mov_b32_dpp v242, v46 row_ror:8 row_mask:0xf bank_mask:0xc
	v_mov_b32_dpp v243, v47 row_ror:8 row_mask:0xf bank_mask:0xc
	v_lshl_add_u64 v[250:251], v[142:143], 0, v[254:255]
	v_lshl_add_u64 v[252:253], v[250:251], 0, s[98:99]
	global_store_dwordx4 v[250:251], v[240:243], off offset:512
	global_store_dwordx4 v[252:253], v[244:247], off offset:512
	v_ashrrev_i64 v[250:251], 1, v[254:255]
	v_lshl_add_u64 v[250:251], v[144:145], 0, v[250:251]
	v_lshl_add_u64 v[252:253], v[250:251], 0, s[100:101]
	v_cvt_pk_bf16_f32 v240, v240, v241
	v_cvt_pk_bf16_f32 v241, v242, v243
	v_cvt_pk_bf16_f32 v244, v244, v245
	v_cvt_pk_bf16_f32 v245, v246, v247
	global_store_dwordx2 v[250:251], v[240:241], off offset:256
	global_store_dwordx2 v[252:253], v[244:245], off offset:256
	v_pk_add_f32 v[52:53], v[52:53], v[114:115]
	s_waitcnt vmcnt(17)
	v_pk_add_f32 v[40:41], v[40:41], v[118:119]
	v_cvt_pk_bf16_f32 v44, v44, v45
	v_cvt_pk_bf16_f32 v45, v46, v47
	v_add_f32_e32 v46, v51, v56
	v_mov_b32_e32 v240, v52
	v_mov_b32_e32 v241, v53
	v_mov_b32_e32 v242, v54
	v_mov_b32_e32 v243, v55
	v_add_f32_e32 v48, v46, v50
	v_cvt_pk_bf16_f32 v44, v52, v53
	v_lshl_add_u64 v[46:47], v[146:147], 1, s[8:9]
	v_cvt_pk_bf16_f32 v45, v54, v55
	v_pk_add_f32 v[42:43], v[42:43], v[120:121]
	v_mul_f32_e32 v44, v41, v41
	v_mov_b32_e32 v244, v40
	v_mov_b32_e32 v245, v41
	v_mov_b32_e32 v246, v42
	v_mov_b32_e32 v247, v43
	v_mov_b32_dpp v244, v240 row_ror:8 row_mask:0xf bank_mask:0x3
	v_mov_b32_dpp v245, v241 row_ror:8 row_mask:0xf bank_mask:0x3
	v_mov_b32_dpp v246, v242 row_ror:8 row_mask:0xf bank_mask:0x3
	v_mov_b32_dpp v247, v243 row_ror:8 row_mask:0xf bank_mask:0x3
	v_mov_b32_dpp v240, v40 row_ror:8 row_mask:0xf bank_mask:0xc
	v_mov_b32_dpp v241, v41 row_ror:8 row_mask:0xf bank_mask:0xc
	v_mov_b32_dpp v242, v42 row_ror:8 row_mask:0xf bank_mask:0xc
	v_mov_b32_dpp v243, v43 row_ror:8 row_mask:0xf bank_mask:0xc
	v_lshl_add_u64 v[250:251], v[92:93], 0, v[254:255]
	v_lshl_add_u64 v[252:253], v[250:251], 0, s[98:99]
	global_store_dwordx4 v[250:251], v[240:243], off
	global_store_dwordx4 v[252:253], v[244:247], off
	v_ashrrev_i64 v[250:251], 1, v[254:255]
	v_lshl_add_u64 v[250:251], v[46:47], 0, v[250:251]
	v_lshl_add_u64 v[252:253], v[250:251], 0, s[100:101]
	v_cvt_pk_bf16_f32 v240, v240, v241
	v_cvt_pk_bf16_f32 v241, v242, v243
	v_cvt_pk_bf16_f32 v244, v244, v245
	v_cvt_pk_bf16_f32 v245, v246, v247
	global_store_dwordx2 v[250:251], v[240:241], off
	global_store_dwordx2 v[252:253], v[244:245], off
	v_fmac_f32_e32 v44, v40, v40
	s_waitcnt vmcnt(20)
	v_pk_add_f32 v[36:37], v[36:37], v[122:123]
	v_cvt_pk_bf16_f32 v40, v40, v41
	v_cvt_pk_bf16_f32 v41, v42, v43
	v_pk_add_f32 v[38:39], v[38:39], v[124:125]
	v_mul_f32_e32 v40, v37, v37
	v_mov_b32_e32 v240, v36
	v_mov_b32_e32 v241, v37
	v_mov_b32_e32 v242, v38
	v_mov_b32_e32 v243, v39
	v_fmac_f32_e32 v40, v36, v36
	s_waitcnt vmcnt(20)
	v_pk_add_f32 v[32:33], v[32:33], v[126:127]
	v_cvt_pk_bf16_f32 v36, v36, v37
	v_cvt_pk_bf16_f32 v37, v38, v39
	v_pk_add_f32 v[34:35], v[34:35], v[128:129]
	v_mul_f32_e32 v36, v33, v33
	v_mov_b32_e32 v244, v32
	v_mov_b32_e32 v245, v33
	v_mov_b32_e32 v246, v34
	v_mov_b32_e32 v247, v35
	v_mov_b32_dpp v244, v240 row_ror:8 row_mask:0xf bank_mask:0x3
	v_mov_b32_dpp v245, v241 row_ror:8 row_mask:0xf bank_mask:0x3
	v_mov_b32_dpp v246, v242 row_ror:8 row_mask:0xf bank_mask:0x3
	v_mov_b32_dpp v247, v243 row_ror:8 row_mask:0xf bank_mask:0x3
	v_mov_b32_dpp v240, v32 row_ror:8 row_mask:0xf bank_mask:0xc
	v_mov_b32_dpp v241, v33 row_ror:8 row_mask:0xf bank_mask:0xc
	v_mov_b32_dpp v242, v34 row_ror:8 row_mask:0xf bank_mask:0xc
	v_mov_b32_dpp v243, v35 row_ror:8 row_mask:0xf bank_mask:0xc
	v_lshl_add_u64 v[250:251], v[92:93], 0, v[254:255]
	v_lshl_add_u64 v[252:253], v[250:251], 0, s[98:99]
	global_store_dwordx4 v[250:251], v[240:243], off offset:512
	global_store_dwordx4 v[252:253], v[244:247], off offset:512
	v_ashrrev_i64 v[250:251], 1, v[254:255]
	v_lshl_add_u64 v[250:251], v[46:47], 0, v[250:251]
	v_lshl_add_u64 v[252:253], v[250:251], 0, s[100:101]
	v_cvt_pk_bf16_f32 v240, v240, v241
	v_cvt_pk_bf16_f32 v241, v242, v243
	v_cvt_pk_bf16_f32 v244, v244, v245
	v_cvt_pk_bf16_f32 v245, v246, v247
	global_store_dwordx2 v[250:251], v[240:241], off offset:256
	global_store_dwordx2 v[252:253], v[244:245], off offset:256
	v_fmac_f32_e32 v36, v32, v32
	v_mul_f32_e32 v37, v35, v35
	v_cvt_pk_bf16_f32 v32, v32, v33
	v_cvt_pk_bf16_f32 v33, v34, v35
	v_lshlrev_b64 v[32:33], 11, v[90:91]
	s_waitcnt vmcnt(23)
	v_pk_add_f32 v[30:31], v[30:31], v[132:133]
	v_pk_add_f32 v[28:29], v[28:29], v[130:131]
	v_fmac_f32_e32 v37, v34, v34
	v_lshl_add_u64 v[32:33], v[32:33], 0, v[164:165]
	v_mul_f32_e32 v34, v29, v29
	v_mul_f32_e32 v35, v31, v31
	v_mov_b32_e32 v240, v28
	v_mov_b32_e32 v241, v29
	v_mov_b32_e32 v242, v30
	v_mov_b32_e32 v243, v31
	v_fmac_f32_e32 v34, v28, v28
	v_fmac_f32_e32 v35, v30, v30
	v_cvt_pk_bf16_f32 v28, v28, v29
	v_cvt_pk_bf16_f32 v29, v30, v31
	v_lshl_add_u64 v[30:31], v[32:33], 1, s[8:9]
	s_waitcnt vmcnt(22)
	v_pk_add_f32 v[24:25], v[24:25], v[134:135]
	v_pk_add_f32 v[26:27], v[26:27], v[136:137]
	v_mul_f32_e32 v28, v25, v25
	v_mov_b32_e32 v244, v24
	v_mov_b32_e32 v245, v25
	v_mov_b32_e32 v246, v26
	v_mov_b32_e32 v247, v27
	v_mov_b32_dpp v244, v240 row_ror:8 row_mask:0xf bank_mask:0x3
	v_mov_b32_dpp v245, v241 row_ror:8 row_mask:0xf bank_mask:0x3
	v_mov_b32_dpp v246, v242 row_ror:8 row_mask:0xf bank_mask:0x3
	v_mov_b32_dpp v247, v243 row_ror:8 row_mask:0xf bank_mask:0x3
	v_mov_b32_dpp v240, v24 row_ror:8 row_mask:0xf bank_mask:0xc
	v_mov_b32_dpp v241, v25 row_ror:8 row_mask:0xf bank_mask:0xc
	v_mov_b32_dpp v242, v26 row_ror:8 row_mask:0xf bank_mask:0xc
	v_mov_b32_dpp v243, v27 row_ror:8 row_mask:0xf bank_mask:0xc
	v_lshl_add_u64 v[250:251], v[94:95], 0, v[254:255]
	v_lshl_add_u64 v[252:253], v[250:251], 0, s[98:99]
	global_store_dwordx4 v[250:251], v[240:243], off
	global_store_dwordx4 v[252:253], v[244:247], off
	v_ashrrev_i64 v[250:251], 1, v[254:255]
	v_lshl_add_u64 v[250:251], v[30:31], 0, v[250:251]
	v_lshl_add_u64 v[252:253], v[250:251], 0, s[100:101]
	v_cvt_pk_bf16_f32 v240, v240, v241
	v_cvt_pk_bf16_f32 v241, v242, v243
	v_cvt_pk_bf16_f32 v244, v244, v245
	v_cvt_pk_bf16_f32 v245, v246, v247
	global_store_dwordx2 v[250:251], v[240:241], off
	global_store_dwordx2 v[252:253], v[244:245], off
	v_fmac_f32_e32 v28, v24, v24
	s_waitcnt vmcnt(24)
	v_pk_add_f32 v[20:21], v[20:21], v[138:139]
	v_cvt_pk_bf16_f32 v24, v24, v25
	v_cvt_pk_bf16_f32 v25, v26, v27
	v_pk_add_f32 v[22:23], v[22:23], v[140:141]
	v_mul_f32_e32 v24, v21, v21
	v_mov_b32_e32 v240, v20
	v_mov_b32_e32 v241, v21
	v_mov_b32_e32 v242, v22
	v_mov_b32_e32 v243, v23
	v_fmac_f32_e32 v24, v20, v20
	s_waitcnt vmcnt(24)
	v_pk_add_f32 v[16:17], v[16:17], v[80:81]
	v_cvt_pk_bf16_f32 v20, v20, v21
	v_cvt_pk_bf16_f32 v21, v22, v23
	v_pk_add_f32 v[18:19], v[18:19], v[82:83]
	v_mul_f32_e32 v20, v17, v17
	v_mov_b32_e32 v244, v16
	v_mov_b32_e32 v245, v17
	v_mov_b32_e32 v246, v18
	v_mov_b32_e32 v247, v19
	v_mov_b32_dpp v244, v240 row_ror:8 row_mask:0xf bank_mask:0x3
	v_mov_b32_dpp v245, v241 row_ror:8 row_mask:0xf bank_mask:0x3
	v_mov_b32_dpp v246, v242 row_ror:8 row_mask:0xf bank_mask:0x3
	v_mov_b32_dpp v247, v243 row_ror:8 row_mask:0xf bank_mask:0x3
	v_mov_b32_dpp v240, v16 row_ror:8 row_mask:0xf bank_mask:0xc
	v_mov_b32_dpp v241, v17 row_ror:8 row_mask:0xf bank_mask:0xc
	v_mov_b32_dpp v242, v18 row_ror:8 row_mask:0xf bank_mask:0xc
	v_mov_b32_dpp v243, v19 row_ror:8 row_mask:0xf bank_mask:0xc
	v_lshl_add_u64 v[250:251], v[94:95], 0, v[254:255]
	v_lshl_add_u64 v[252:253], v[250:251], 0, s[98:99]
	global_store_dwordx4 v[250:251], v[240:243], off offset:512
	global_store_dwordx4 v[252:253], v[244:247], off offset:512
	v_ashrrev_i64 v[250:251], 1, v[254:255]
	v_lshl_add_u64 v[250:251], v[30:31], 0, v[250:251]
	v_lshl_add_u64 v[252:253], v[250:251], 0, s[100:101]
	v_cvt_pk_bf16_f32 v240, v240, v241
	v_cvt_pk_bf16_f32 v241, v242, v243
	v_cvt_pk_bf16_f32 v244, v244, v245
	v_cvt_pk_bf16_f32 v245, v246, v247
	global_store_dwordx2 v[250:251], v[240:241], off offset:256
	global_store_dwordx2 v[252:253], v[244:245], off offset:256
	v_fmac_f32_e32 v20, v16, v16
	v_mul_f32_e32 v21, v19, v19
	v_cvt_pk_bf16_f32 v16, v16, v17
	v_cvt_pk_bf16_f32 v17, v18, v19
	v_lshlrev_b64 v[16:17], 11, v[88:89]
	s_waitcnt vmcnt(27)
	v_pk_add_f32 v[14:15], v[14:15], v[78:79]
	v_pk_add_f32 v[12:13], v[12:13], v[76:77]
	v_fmac_f32_e32 v21, v18, v18
	v_lshl_add_u64 v[16:17], v[16:17], 0, v[164:165]
	v_mul_f32_e32 v18, v13, v13
	v_mul_f32_e32 v19, v15, v15
	v_mov_b32_e32 v240, v12
	v_mov_b32_e32 v241, v13
	v_mov_b32_e32 v242, v14
	v_mov_b32_e32 v243, v15
	v_fmac_f32_e32 v18, v12, v12
	v_fmac_f32_e32 v19, v14, v14
	v_cvt_pk_bf16_f32 v12, v12, v13
	v_cvt_pk_bf16_f32 v13, v14, v15
	v_lshl_add_u64 v[14:15], v[16:17], 1, s[8:9]
	s_waitcnt vmcnt(26)
	v_pk_add_f32 v[8:9], v[8:9], v[72:73]
	v_pk_add_f32 v[10:11], v[10:11], v[74:75]
	v_mul_f32_e32 v12, v9, v9
	v_mov_b32_e32 v244, v8
	v_mov_b32_e32 v245, v9
	v_mov_b32_e32 v246, v10
	v_mov_b32_e32 v247, v11
	v_mov_b32_dpp v244, v240 row_ror:8 row_mask:0xf bank_mask:0x3
	v_mov_b32_dpp v245, v241 row_ror:8 row_mask:0xf bank_mask:0x3
	v_mov_b32_dpp v246, v242 row_ror:8 row_mask:0xf bank_mask:0x3
	v_mov_b32_dpp v247, v243 row_ror:8 row_mask:0xf bank_mask:0x3
	v_mov_b32_dpp v240, v8 row_ror:8 row_mask:0xf bank_mask:0xc
	v_mov_b32_dpp v241, v9 row_ror:8 row_mask:0xf bank_mask:0xc
	v_mov_b32_dpp v242, v10 row_ror:8 row_mask:0xf bank_mask:0xc
	v_mov_b32_dpp v243, v11 row_ror:8 row_mask:0xf bank_mask:0xc
	v_lshl_add_u64 v[250:251], v[86:87], 0, v[254:255]
	v_lshl_add_u64 v[252:253], v[250:251], 0, s[98:99]
	global_store_dwordx4 v[250:251], v[240:243], off
	global_store_dwordx4 v[252:253], v[244:247], off
	v_ashrrev_i64 v[250:251], 1, v[254:255]
	v_lshl_add_u64 v[250:251], v[14:15], 0, v[250:251]
	v_lshl_add_u64 v[252:253], v[250:251], 0, s[100:101]
	v_cvt_pk_bf16_f32 v240, v240, v241
	v_cvt_pk_bf16_f32 v241, v242, v243
	v_cvt_pk_bf16_f32 v244, v244, v245
	v_cvt_pk_bf16_f32 v245, v246, v247
	global_store_dwordx2 v[250:251], v[240:241], off
	global_store_dwordx2 v[252:253], v[244:245], off
	v_fmac_f32_e32 v12, v8, v8
	v_mul_f32_e32 v13, v11, v11
	v_cvt_pk_bf16_f32 v8, v8, v9
	v_cvt_pk_bf16_f32 v9, v10, v11
	s_waitcnt vmcnt(28)
	v_pk_add_f32 v[6:7], v[6:7], v[70:71]
	v_pk_add_f32 v[4:5], v[4:5], v[68:69]
	v_fmac_f32_e32 v13, v10, v10
	v_mul_f32_e32 v8, v5, v5
	v_mul_f32_e32 v9, v7, v7
	v_add_f32_e32 v18, v18, v19
	v_add_f32_e32 v12, v12, v13
	v_fmac_f32_e32 v8, v4, v4
	v_fmac_f32_e32 v9, v6, v6
	v_mul_f32_e32 v106, v53, v53
	v_mul_f32_e32 v107, v55, v55
	v_mul_f32_e32 v45, v43, v43
	v_mul_f32_e32 v29, v27, v27
	v_add_f32_e32 v12, v18, v12
	v_add_f32_e32 v8, v8, v9
	v_fmac_f32_e32 v106, v52, v52
	v_fmac_f32_e32 v107, v54, v54
	v_fmac_f32_e32 v45, v42, v42
	v_mul_f32_e32 v41, v39, v39
	v_fmac_f32_e32 v29, v26, v26
	v_mul_f32_e32 v25, v23, v23
	v_add_f32_e32 v12, v12, v8
	s_waitcnt vmcnt(28)
	v_pk_add_f32 v[10:11], v[2:3], v[66:67]
	v_pk_add_f32 v[8:9], v[0:1], v[64:65]
	v_add_f32_e32 v49, v106, v107
	v_add_f32_e32 v44, v44, v45
	v_fmac_f32_e32 v41, v38, v38
	v_add_f32_e32 v34, v34, v35
	v_add_f32_e32 v28, v28, v29
	v_fmac_f32_e32 v25, v22, v22
	v_mul_f32_e32 v0, v9, v9
	v_mul_f32_e32 v1, v11, v11
	v_add_f32_e32 v44, v49, v44
	v_add_f32_e32 v40, v40, v41
	v_add_f32_e32 v28, v34, v28
	v_add_f32_e32 v24, v24, v25
	v_fmac_f32_e32 v0, v8, v8
	v_fmac_f32_e32 v1, v10, v10
	v_add_f32_e32 v40, v44, v40
	v_add_f32_e32 v36, v36, v37
	v_add_f32_e32 v24, v28, v24
	v_add_f32_e32 v20, v20, v21
	v_add_f32_e32 v0, v0, v1
	v_add_f32_e32 v36, v40, v36
	v_add_f32_e32 v20, v24, v20
	v_add_f32_e32 v3, v12, v0
	v_mov_b32_e32 v240, v4
	v_mov_b32_e32 v241, v5
	v_mov_b32_e32 v242, v6
	v_mov_b32_e32 v243, v7
	ds_bpermute_b32 v0, v96, v48
	ds_bpermute_b32 v1, v96, v36
	v_cvt_pk_bf16_f32 v4, v4, v5
	v_cvt_pk_bf16_f32 v5, v6, v7
	ds_bpermute_b32 v2, v96, v20
	ds_bpermute_b32 v6, v96, v3
	s_waitcnt lgkmcnt(3)
	v_add_f32_e32 v0, v48, v0
	s_waitcnt lgkmcnt(2)
	v_add_f32_e32 v1, v36, v1
	s_waitcnt lgkmcnt(1)
	v_add_f32_e32 v2, v20, v2
	s_waitcnt lgkmcnt(0)
	v_add_f32_e32 v4, v3, v6
	ds_bpermute_b32 v3, v97, v0
	ds_bpermute_b32 v5, v97, v1
	ds_bpermute_b32 v6, v97, v2
	ds_bpermute_b32 v7, v97, v4
	v_mov_b32_e32 v244, v8
	v_mov_b32_e32 v245, v9
	v_mov_b32_e32 v246, v10
	v_mov_b32_e32 v247, v11
	v_mov_b32_dpp v244, v240 row_ror:8 row_mask:0xf bank_mask:0x3
	v_mov_b32_dpp v245, v241 row_ror:8 row_mask:0xf bank_mask:0x3
	v_mov_b32_dpp v246, v242 row_ror:8 row_mask:0xf bank_mask:0x3
	v_mov_b32_dpp v247, v243 row_ror:8 row_mask:0xf bank_mask:0x3
	v_mov_b32_dpp v240, v8 row_ror:8 row_mask:0xf bank_mask:0xc
	v_mov_b32_dpp v241, v9 row_ror:8 row_mask:0xf bank_mask:0xc
	v_mov_b32_dpp v242, v10 row_ror:8 row_mask:0xf bank_mask:0xc
	v_mov_b32_dpp v243, v11 row_ror:8 row_mask:0xf bank_mask:0xc
	v_lshl_add_u64 v[250:251], v[86:87], 0, v[254:255]
	v_lshl_add_u64 v[252:253], v[250:251], 0, s[98:99]
	global_store_dwordx4 v[250:251], v[240:243], off offset:512
	global_store_dwordx4 v[252:253], v[244:247], off offset:512
	v_ashrrev_i64 v[250:251], 1, v[254:255]
	v_lshl_add_u64 v[250:251], v[14:15], 0, v[250:251]
	v_lshl_add_u64 v[252:253], v[250:251], 0, s[100:101]
	v_cvt_pk_bf16_f32 v240, v240, v241
	v_cvt_pk_bf16_f32 v241, v242, v243
	v_cvt_pk_bf16_f32 v244, v244, v245
	v_cvt_pk_bf16_f32 v245, v246, v247
	global_store_dwordx2 v[250:251], v[240:241], off offset:256
	global_store_dwordx2 v[252:253], v[244:245], off offset:256
	s_nop 1
	v_cvt_pk_bf16_f32 v8, v8, v9
	v_cvt_pk_bf16_f32 v9, v10, v11
	s_and_saveexec_b64 s[38:39], s[2:3]
	s_cbranch_execz .LBB0_999
	s_waitcnt lgkmcnt(3)
	v_add_f32_e32 v0, v0, v3
	s_waitcnt lgkmcnt(0)
	v_add_f32_e32 v4, v4, v7
	v_add_f32_e32 v2, v2, v6
	v_add_f32_e32 v1, v1, v5
	global_atomic_add_f32 v[84:85], v0, off offset:512
	global_atomic_add_f32 v[84:85], v1, off offset:576
	global_atomic_add_f32 v[84:85], v2, off offset:640
	global_atomic_add_f32 v[84:85], v4, off offset:704

.LBB0_1476:
	s_mov_b32 s98, 0x10000
	s_mov_b32 s99, 0
	s_mov_b32 s100, 0x8000
	s_mov_b32 s101, 0
	v_bfe_u32 v255, v220, 3, 1
	v_sub_u32_e32 v255, 0, v255
	v_and_b32_e32 v254, 0xffff0040, v255
	v_lshl_add_u32 v168, s67, 8, v180
	v_lshl_or_b32 v164, s68, 8, v182
	v_readlane_b32 s68, v248, 0
	v_ashrrev_i32_e32 v165, 31, v164
	v_ashrrev_i32_e32 v169, 31, v168
	v_readlane_b32 s74, v248, 6
	v_readlane_b32 s75, v248, 7
	v_lshlrev_b64 v[128:129], 13, v[168:169]
	v_or_b32_e32 v174, 32, v168
	v_lshl_add_u64 v[166:167], v[164:165], 2, s[74:75]
	v_lshl_add_u64 v[218:219], v[166:167], 0, v[128:129]
	v_or_b32_e32 v128, 16, v168
	v_ashrrev_i32_e32 v129, 31, v128
	global_load_dwordx4 v[186:189], v[218:219], off
	global_load_dwordx4 v[190:193], v[218:219], off offset:64
	global_load_dwordx4 v[194:197], v[218:219], off offset:512
	global_load_dwordx4 v[198:201], v[218:219], off offset:576
	v_lshlrev_b64 v[130:131], 13, v[128:129]
	v_lshl_add_u64 v[176:177], v[166:167], 0, v[130:131]
	global_load_dwordx4 v[202:205], v[176:177], off
	global_load_dwordx4 v[206:209], v[176:177], off offset:64
	v_or_b32_e32 v170, 48, v168
	v_ashrrev_i32_e32 v175, 31, v174
	v_ashrrev_i32_e32 v171, 31, v170
	v_lshlrev_b64 v[130:131], 11, v[168:169]
	v_lshlrev_b64 v[132:133], 13, v[174:175]
	v_lshlrev_b64 v[134:135], 13, v[170:171]
	v_lshl_add_u64 v[130:131], v[130:131], 0, v[164:165]
	v_lshlrev_b64 v[128:129], 11, v[128:129]
	v_lshl_add_u64 v[178:179], v[166:167], 0, v[132:133]
	v_lshl_add_u64 v[172:173], v[166:167], 0, v[134:135]
	v_lshl_add_u64 v[234:235], v[130:131], 1, s[10:11]
	v_lshl_add_u64 v[236:237], v[128:129], 0, v[164:165]
	global_load_dwordx4 v[210:213], v[176:177], off offset:512
	global_load_dwordx4 v[214:217], v[176:177], off offset:576
	global_load_dwordx4 v[222:225], v[178:179], off
	global_load_dwordx4 v[226:229], v[178:179], off offset:64
	global_load_dwordx4 v[230:233], v[178:179], off offset:512
	global_load_dwordx4 v[144:147], v[178:179], off offset:576
	global_load_dwordx4 v[140:143], v[172:173], off
	global_load_dwordx4 v[136:139], v[172:173], off offset:64
	global_load_dwordx4 v[132:135], v[172:173], off offset:512
	global_load_dwordx4 v[128:131], v[172:173], off offset:576
	v_readlane_b32 s69, v248, 1
	v_readlane_b32 s70, v248, 2
	v_readlane_b32 s71, v248, 3
	v_readlane_b32 s72, v248, 4
	v_readlane_b32 s73, v248, 5
	s_waitcnt vmcnt(0)
	v_pk_add_f32 v[126:127], v[126:127], v[188:189]
	v_pk_add_f32 v[124:125], v[124:125], v[186:187]
	v_pk_add_f32 v[120:121], v[120:121], v[190:191]
	v_pk_add_f32 v[122:123], v[122:123], v[192:193]
	v_pk_add_f32 v[112:113], v[112:113], v[194:195]
	v_mov_b32_e32 v240, v124
	v_mov_b32_e32 v241, v125
	v_mov_b32_e32 v242, v126
	v_mov_b32_e32 v243, v127
	v_mul_f32_e32 v188, v125, v125
	v_cvt_pk_bf16_f32 v186, v124, v125
	v_cvt_pk_bf16_f32 v187, v126, v127
	v_pk_add_f32 v[114:115], v[114:115], v[196:197]
	v_mul_f32_e32 v125, v121, v121
	v_pk_add_f32 v[108:109], v[108:109], v[198:199]
	v_mul_f32_e32 v189, v127, v127
	v_mul_f32_e32 v127, v123, v123
	v_mul_f32_e32 v190, v113, v113
	v_mov_b32_e32 v244, v120
	v_mov_b32_e32 v245, v121
	v_mov_b32_e32 v246, v122
	v_mov_b32_e32 v247, v123
	v_mov_b32_dpp v244, v240 row_ror:8 row_mask:0xf bank_mask:0x3
	v_mov_b32_dpp v245, v241 row_ror:8 row_mask:0xf bank_mask:0x3
	v_mov_b32_dpp v246, v242 row_ror:8 row_mask:0xf bank_mask:0x3
	v_mov_b32_dpp v247, v243 row_ror:8 row_mask:0xf bank_mask:0x3
	v_mov_b32_dpp v240, v120 row_ror:8 row_mask:0xf bank_mask:0xc
	v_mov_b32_dpp v241, v121 row_ror:8 row_mask:0xf bank_mask:0xc
	v_mov_b32_dpp v242, v122 row_ror:8 row_mask:0xf bank_mask:0xc
	v_mov_b32_dpp v243, v123 row_ror:8 row_mask:0xf bank_mask:0xc
	v_lshl_add_u64 v[250:251], v[218:219], 0, v[254:255]
	v_lshl_add_u64 v[252:253], v[250:251], 0, s[98:99]
	global_store_dwordx4 v[250:251], v[240:243], off
	global_store_dwordx4 v[252:253], v[244:247], off
	v_ashrrev_i64 v[250:251], 1, v[254:255]
	v_lshl_add_u64 v[250:251], v[234:235], 0, v[250:251]
	v_lshl_add_u64 v[252:253], v[250:251], 0, s[100:101]
	v_cvt_pk_bf16_f32 v240, v240, v241
	v_cvt_pk_bf16_f32 v241, v242, v243
	v_cvt_pk_bf16_f32 v244, v244, v245
	v_cvt_pk_bf16_f32 v245, v246, v247
	global_store_dwordx2 v[250:251], v[240:241], off
	global_store_dwordx2 v[252:253], v[244:245], off
	v_fmac_f32_e32 v125, v120, v120
	v_pk_add_f32 v[110:111], v[110:111], v[200:201]
	v_cvt_pk_bf16_f32 v120, v120, v121
	v_cvt_pk_bf16_f32 v121, v122, v123
	v_mul_f32_e32 v191, v115, v115
	v_mul_f32_e32 v192, v109, v109
	v_fmac_f32_e32 v188, v124, v124
	v_fmac_f32_e32 v189, v126, v126
	v_fmac_f32_e32 v127, v122, v122
	v_fmac_f32_e32 v190, v112, v112
	v_mov_b32_e32 v240, v112
	v_mov_b32_e32 v241, v113
	v_mov_b32_e32 v242, v114
	v_mov_b32_e32 v243, v115
	v_mul_f32_e32 v193, v111, v111
	v_pk_add_f32 v[118:119], v[118:119], v[204:205]
	v_cvt_pk_bf16_f32 v112, v112, v113
	v_cvt_pk_bf16_f32 v113, v114, v115
	v_pk_add_f32 v[116:117], v[116:117], v[202:203]
	v_fmac_f32_e32 v191, v114, v114
	v_fmac_f32_e32 v192, v108, v108
	v_add_f32_e32 v123, v188, v189
	v_add_f32_e32 v124, v125, v127
	v_mov_b32_e32 v244, v108
	v_mov_b32_e32 v245, v109
	v_mov_b32_e32 v246, v110
	v_mov_b32_e32 v247, v111
	v_mov_b32_dpp v244, v240 row_ror:8 row_mask:0xf bank_mask:0x3
	v_mov_b32_dpp v245, v241 row_ror:8 row_mask:0xf bank_mask:0x3
	v_mov_b32_dpp v246, v242 row_ror:8 row_mask:0xf bank_mask:0x3
	v_mov_b32_dpp v247, v243 row_ror:8 row_mask:0xf bank_mask:0x3
	v_mov_b32_dpp v240, v108 row_ror:8 row_mask:0xf bank_mask:0xc
	v_mov_b32_dpp v241, v109 row_ror:8 row_mask:0xf bank_mask:0xc
	v_mov_b32_dpp v242, v110 row_ror:8 row_mask:0xf bank_mask:0xc
	v_mov_b32_dpp v243, v111 row_ror:8 row_mask:0xf bank_mask:0xc
	v_lshl_add_u64 v[250:251], v[218:219], 0, v[254:255]
	v_lshl_add_u64 v[252:253], v[250:251], 0, s[98:99]
	global_store_dwordx4 v[250:251], v[240:243], off offset:512
	global_store_dwordx4 v[252:253], v[244:247], off offset:512
	v_ashrrev_i64 v[250:251], 1, v[254:255]
	v_lshl_add_u64 v[250:251], v[234:235], 0, v[250:251]
	v_lshl_add_u64 v[252:253], v[250:251], 0, s[100:101]
	v_cvt_pk_bf16_f32 v240, v240, v241
	v_cvt_pk_bf16_f32 v241, v242, v243
	v_cvt_pk_bf16_f32 v244, v244, v245
	v_cvt_pk_bf16_f32 v245, v246, v247
	global_store_dwordx2 v[250:251], v[240:241], off offset:256
	global_store_dwordx2 v[252:253], v[244:245], off offset:256
	v_fmac_f32_e32 v193, v110, v110
	v_mul_f32_e32 v122, v117, v117
	v_cvt_pk_bf16_f32 v108, v108, v109
	v_cvt_pk_bf16_f32 v109, v110, v111
	v_add_f32_e32 v120, v190, v191
	v_add_f32_e32 v115, v123, v124
	v_mov_b32_e32 v240, v116
	v_mov_b32_e32 v241, v117
	v_mov_b32_e32 v242, v118
	v_mov_b32_e32 v243, v119
	v_mul_f32_e32 v108, v119, v119
	v_add_f32_e32 v114, v192, v193
	v_add_f32_e32 v110, v115, v120
	v_fmac_f32_e32 v122, v116, v116
	v_fmac_f32_e32 v108, v118, v118
	v_add_f32_e32 v112, v110, v114
	v_add_f32_e32 v113, v122, v108
	v_cvt_pk_bf16_f32 v108, v116, v117
	v_lshl_add_u64 v[110:111], v[236:237], 1, s[10:11]
	v_pk_add_f32 v[104:105], v[104:105], v[206:207]
	v_cvt_pk_bf16_f32 v109, v118, v119
	v_pk_add_f32 v[106:107], v[106:107], v[208:209]
	v_mul_f32_e32 v108, v105, v105
	v_mov_b32_e32 v244, v104
	v_mov_b32_e32 v245, v105
	v_mov_b32_e32 v246, v106
	v_mov_b32_e32 v247, v107
	v_mov_b32_dpp v244, v240 row_ror:8 row_mask:0xf bank_mask:0x3
	v_mov_b32_dpp v245, v241 row_ror:8 row_mask:0xf bank_mask:0x3
	v_mov_b32_dpp v246, v242 row_ror:8 row_mask:0xf bank_mask:0x3
	v_mov_b32_dpp v247, v243 row_ror:8 row_mask:0xf bank_mask:0x3
	v_mov_b32_dpp v240, v104 row_ror:8 row_mask:0xf bank_mask:0xc
	v_mov_b32_dpp v241, v105 row_ror:8 row_mask:0xf bank_mask:0xc
	v_mov_b32_dpp v242, v106 row_ror:8 row_mask:0xf bank_mask:0xc
	v_mov_b32_dpp v243, v107 row_ror:8 row_mask:0xf bank_mask:0xc
	v_lshl_add_u64 v[250:251], v[176:177], 0, v[254:255]
	v_lshl_add_u64 v[252:253], v[250:251], 0, s[98:99]
	global_store_dwordx4 v[250:251], v[240:243], off
	global_store_dwordx4 v[252:253], v[244:247], off
	v_ashrrev_i64 v[250:251], 1, v[254:255]
	v_lshl_add_u64 v[250:251], v[110:111], 0, v[250:251]
	v_lshl_add_u64 v[252:253], v[250:251], 0, s[100:101]
	v_cvt_pk_bf16_f32 v240, v240, v241
	v_cvt_pk_bf16_f32 v241, v242, v243
	v_cvt_pk_bf16_f32 v244, v244, v245
	v_cvt_pk_bf16_f32 v245, v246, v247
	global_store_dwordx2 v[250:251], v[240:241], off
	global_store_dwordx2 v[252:253], v[244:245], off
	v_fmac_f32_e32 v108, v104, v104
	v_pk_add_f32 v[100:101], v[100:101], v[210:211]
	v_cvt_pk_bf16_f32 v104, v104, v105
	v_cvt_pk_bf16_f32 v105, v106, v107
	v_pk_add_f32 v[102:103], v[102:103], v[212:213]
	v_mul_f32_e32 v104, v101, v101
	v_mov_b32_e32 v240, v100
	v_mov_b32_e32 v241, v101
	v_mov_b32_e32 v242, v102
	v_mov_b32_e32 v243, v103
	v_fmac_f32_e32 v104, v100, v100
	v_pk_add_f32 v[96:97], v[96:97], v[214:215]
	v_cvt_pk_bf16_f32 v100, v100, v101
	v_cvt_pk_bf16_f32 v101, v102, v103
	v_pk_add_f32 v[98:99], v[98:99], v[216:217]
	v_mul_f32_e32 v100, v97, v97
	v_mov_b32_e32 v244, v96
	v_mov_b32_e32 v245, v97
	v_mov_b32_e32 v246, v98
	v_mov_b32_e32 v247, v99
	v_mov_b32_dpp v244, v240 row_ror:8 row_mask:0xf bank_mask:0x3
	v_mov_b32_dpp v245, v241 row_ror:8 row_mask:0xf bank_mask:0x3
	v_mov_b32_dpp v246, v242 row_ror:8 row_mask:0xf bank_mask:0x3
	v_mov_b32_dpp v247, v243 row_ror:8 row_mask:0xf bank_mask:0x3
	v_mov_b32_dpp v240, v96 row_ror:8 row_mask:0xf bank_mask:0xc
	v_mov_b32_dpp v241, v97 row_ror:8 row_mask:0xf bank_mask:0xc
	v_mov_b32_dpp v242, v98 row_ror:8 row_mask:0xf bank_mask:0xc
	v_mov_b32_dpp v243, v99 row_ror:8 row_mask:0xf bank_mask:0xc
	v_lshl_add_u64 v[250:251], v[176:177], 0, v[254:255]
	v_lshl_add_u64 v[252:253], v[250:251], 0, s[98:99]
	global_store_dwordx4 v[250:251], v[240:243], off offset:512
	global_store_dwordx4 v[252:253], v[244:247], off offset:512
	v_ashrrev_i64 v[250:251], 1, v[254:255]
	v_lshl_add_u64 v[250:251], v[110:111], 0, v[250:251]
	v_lshl_add_u64 v[252:253], v[250:251], 0, s[100:101]
	v_cvt_pk_bf16_f32 v240, v240, v241
	v_cvt_pk_bf16_f32 v241, v242, v243
	v_cvt_pk_bf16_f32 v244, v244, v245
	v_cvt_pk_bf16_f32 v245, v246, v247
	global_store_dwordx2 v[250:251], v[240:241], off offset:256
	global_store_dwordx2 v[252:253], v[244:245], off offset:256
	v_fmac_f32_e32 v100, v96, v96
	v_mul_f32_e32 v101, v99, v99
	v_cvt_pk_bf16_f32 v96, v96, v97
	v_cvt_pk_bf16_f32 v97, v98, v99
	v_lshlrev_b64 v[96:97], 11, v[174:175]
	v_pk_add_f32 v[94:95], v[94:95], v[224:225]
	v_pk_add_f32 v[92:93], v[92:93], v[222:223]
	v_fmac_f32_e32 v101, v98, v98
	v_lshl_add_u64 v[96:97], v[96:97], 0, v[164:165]
	v_mul_f32_e32 v98, v93, v93
	v_mul_f32_e32 v99, v95, v95
	v_mov_b32_e32 v240, v92
	v_mov_b32_e32 v241, v93
	v_mov_b32_e32 v242, v94
	v_mov_b32_e32 v243, v95
	v_fmac_f32_e32 v98, v92, v92
	v_fmac_f32_e32 v99, v94, v94
	v_cvt_pk_bf16_f32 v92, v92, v93
	v_cvt_pk_bf16_f32 v93, v94, v95
	v_lshl_add_u64 v[94:95], v[96:97], 1, s[10:11]
	v_pk_add_f32 v[88:89], v[88:89], v[226:227]
	v_pk_add_f32 v[90:91], v[90:91], v[228:229]
	v_mul_f32_e32 v92, v89, v89
	v_mov_b32_e32 v244, v88
	v_mov_b32_e32 v245, v89
	v_mov_b32_e32 v246, v90
	v_mov_b32_e32 v247, v91
	v_mov_b32_dpp v244, v240 row_ror:8 row_mask:0xf bank_mask:0x3
	v_mov_b32_dpp v245, v241 row_ror:8 row_mask:0xf bank_mask:0x3
	v_mov_b32_dpp v246, v242 row_ror:8 row_mask:0xf bank_mask:0x3
	v_mov_b32_dpp v247, v243 row_ror:8 row_mask:0xf bank_mask:0x3
	v_mov_b32_dpp v240, v88 row_ror:8 row_mask:0xf bank_mask:0xc
	v_mov_b32_dpp v241, v89 row_ror:8 row_mask:0xf bank_mask:0xc
	v_mov_b32_dpp v242, v90 row_ror:8 row_mask:0xf bank_mask:0xc
	v_mov_b32_dpp v243, v91 row_ror:8 row_mask:0xf bank_mask:0xc
	v_lshl_add_u64 v[250:251], v[178:179], 0, v[254:255]
	v_lshl_add_u64 v[252:253], v[250:251], 0, s[98:99]
	global_store_dwordx4 v[250:251], v[240:243], off
	global_store_dwordx4 v[252:253], v[244:247], off
	v_ashrrev_i64 v[250:251], 1, v[254:255]
	v_lshl_add_u64 v[250:251], v[94:95], 0, v[250:251]
	v_lshl_add_u64 v[252:253], v[250:251], 0, s[100:101]
	v_cvt_pk_bf16_f32 v240, v240, v241
	v_cvt_pk_bf16_f32 v241, v242, v243
	v_cvt_pk_bf16_f32 v244, v244, v245
	v_cvt_pk_bf16_f32 v245, v246, v247
	global_store_dwordx2 v[250:251], v[240:241], off
	global_store_dwordx2 v[252:253], v[244:245], off
	v_fmac_f32_e32 v92, v88, v88
	v_pk_add_f32 v[84:85], v[84:85], v[230:231]
	v_cvt_pk_bf16_f32 v88, v88, v89
	v_cvt_pk_bf16_f32 v89, v90, v91
	v_pk_add_f32 v[86:87], v[86:87], v[232:233]
	v_mul_f32_e32 v88, v85, v85
	v_mov_b32_e32 v240, v84
	v_mov_b32_e32 v241, v85
	v_mov_b32_e32 v242, v86
	v_mov_b32_e32 v243, v87
	v_fmac_f32_e32 v88, v84, v84
	v_pk_add_f32 v[80:81], v[80:81], v[144:145]
	v_cvt_pk_bf16_f32 v84, v84, v85
	v_cvt_pk_bf16_f32 v85, v86, v87
	v_pk_add_f32 v[82:83], v[82:83], v[146:147]
	v_mul_f32_e32 v84, v81, v81
	v_mov_b32_e32 v244, v80
	v_mov_b32_e32 v245, v81
	v_mov_b32_e32 v246, v82
	v_mov_b32_e32 v247, v83
	v_mov_b32_dpp v244, v240 row_ror:8 row_mask:0xf bank_mask:0x3
	v_mov_b32_dpp v245, v241 row_ror:8 row_mask:0xf bank_mask:0x3
	v_mov_b32_dpp v246, v242 row_ror:8 row_mask:0xf bank_mask:0x3
	v_mov_b32_dpp v247, v243 row_ror:8 row_mask:0xf bank_mask:0x3
	v_mov_b32_dpp v240, v80 row_ror:8 row_mask:0xf bank_mask:0xc
	v_mov_b32_dpp v241, v81 row_ror:8 row_mask:0xf bank_mask:0xc
	v_mov_b32_dpp v242, v82 row_ror:8 row_mask:0xf bank_mask:0xc
	v_mov_b32_dpp v243, v83 row_ror:8 row_mask:0xf bank_mask:0xc
	v_lshl_add_u64 v[250:251], v[178:179], 0, v[254:255]
	v_lshl_add_u64 v[252:253], v[250:251], 0, s[98:99]
	global_store_dwordx4 v[250:251], v[240:243], off offset:512
	global_store_dwordx4 v[252:253], v[244:247], off offset:512
	v_ashrrev_i64 v[250:251], 1, v[254:255]
	v_lshl_add_u64 v[250:251], v[94:95], 0, v[250:251]
	v_lshl_add_u64 v[252:253], v[250:251], 0, s[100:101]
	v_cvt_pk_bf16_f32 v240, v240, v241
	v_cvt_pk_bf16_f32 v241, v242, v243
	v_cvt_pk_bf16_f32 v244, v244, v245
	v_cvt_pk_bf16_f32 v245, v246, v247
	global_store_dwordx2 v[250:251], v[240:241], off offset:256
	global_store_dwordx2 v[252:253], v[244:245], off offset:256
	v_fmac_f32_e32 v84, v80, v80
	v_mul_f32_e32 v85, v83, v83
	v_cvt_pk_bf16_f32 v80, v80, v81
	v_cvt_pk_bf16_f32 v81, v82, v83
	v_lshlrev_b64 v[80:81], 11, v[170:171]
	v_pk_add_f32 v[78:79], v[78:79], v[142:143]
	v_pk_add_f32 v[76:77], v[76:77], v[140:141]
	v_fmac_f32_e32 v85, v82, v82
	v_lshl_add_u64 v[80:81], v[80:81], 0, v[164:165]
	v_mul_f32_e32 v82, v77, v77
	v_mul_f32_e32 v83, v79, v79
	v_mov_b32_e32 v240, v76
	v_mov_b32_e32 v241, v77
	v_mov_b32_e32 v242, v78
	v_mov_b32_e32 v243, v79
	v_fmac_f32_e32 v82, v76, v76
	v_fmac_f32_e32 v83, v78, v78
	v_cvt_pk_bf16_f32 v76, v76, v77
	v_cvt_pk_bf16_f32 v77, v78, v79
	v_lshl_add_u64 v[78:79], v[80:81], 1, s[10:11]
	v_pk_add_f32 v[72:73], v[72:73], v[136:137]
	v_pk_add_f32 v[74:75], v[74:75], v[138:139]
	v_mul_f32_e32 v76, v73, v73
	v_mov_b32_e32 v244, v72
	v_mov_b32_e32 v245, v73
	v_mov_b32_e32 v246, v74
	v_mov_b32_e32 v247, v75
	v_mov_b32_dpp v244, v240 row_ror:8 row_mask:0xf bank_mask:0x3
	v_mov_b32_dpp v245, v241 row_ror:8 row_mask:0xf bank_mask:0x3
	v_mov_b32_dpp v246, v242 row_ror:8 row_mask:0xf bank_mask:0x3
	v_mov_b32_dpp v247, v243 row_ror:8 row_mask:0xf bank_mask:0x3
	v_mov_b32_dpp v240, v72 row_ror:8 row_mask:0xf bank_mask:0xc
	v_mov_b32_dpp v241, v73 row_ror:8 row_mask:0xf bank_mask:0xc
	v_mov_b32_dpp v242, v74 row_ror:8 row_mask:0xf bank_mask:0xc
	v_mov_b32_dpp v243, v75 row_ror:8 row_mask:0xf bank_mask:0xc
	v_lshl_add_u64 v[250:251], v[172:173], 0, v[254:255]
	v_lshl_add_u64 v[252:253], v[250:251], 0, s[98:99]
	global_store_dwordx4 v[250:251], v[240:243], off
	global_store_dwordx4 v[252:253], v[244:247], off
	v_ashrrev_i64 v[250:251], 1, v[254:255]
	v_lshl_add_u64 v[250:251], v[78:79], 0, v[250:251]
	v_lshl_add_u64 v[252:253], v[250:251], 0, s[100:101]
	v_cvt_pk_bf16_f32 v240, v240, v241
	v_cvt_pk_bf16_f32 v241, v242, v243
	v_cvt_pk_bf16_f32 v244, v244, v245
	v_cvt_pk_bf16_f32 v245, v246, v247
	global_store_dwordx2 v[250:251], v[240:241], off
	global_store_dwordx2 v[252:253], v[244:245], off
	v_fmac_f32_e32 v76, v72, v72
	v_mul_f32_e32 v77, v75, v75
	v_cvt_pk_bf16_f32 v72, v72, v73
	v_cvt_pk_bf16_f32 v73, v74, v75
	v_pk_add_f32 v[70:71], v[70:71], v[134:135]
	v_pk_add_f32 v[68:69], v[68:69], v[132:133]
	v_fmac_f32_e32 v77, v74, v74
	v_mul_f32_e32 v72, v69, v69
	v_mul_f32_e32 v73, v71, v71
	v_add_f32_e32 v82, v82, v83
	v_add_f32_e32 v76, v76, v77
	v_fmac_f32_e32 v72, v68, v68
	v_fmac_f32_e32 v73, v70, v70
	v_add_f32_e32 v76, v82, v76
	v_add_f32_e32 v72, v72, v73
	v_add_f32_e32 v76, v76, v72
	v_pk_add_f32 v[74:75], v[66:67], v[130:131]
	v_pk_add_f32 v[72:73], v[64:65], v[128:129]
	v_mul_f32_e32 v65, v75, v75
	v_mul_f32_e32 v64, v73, v73
	v_fmac_f32_e32 v64, v72, v72
	v_fmac_f32_e32 v65, v74, v74
	v_mov_b32_e32 v240, v68
	v_mov_b32_e32 v241, v69
	v_mov_b32_e32 v242, v70
	v_mov_b32_e32 v243, v71
	v_add_f32_e32 v64, v64, v65
	v_and_b32_e32 v65, 64, v185
	v_cvt_pk_bf16_f32 v68, v68, v69
	v_cvt_pk_bf16_f32 v69, v70, v71
	v_add_f32_e32 v67, v76, v64
	v_xor_b32_e32 v64, 16, v185
	v_add_u32_e32 v68, 64, v65
	v_mul_f32_e32 v109, v107, v107
	v_mul_f32_e32 v93, v91, v91
	v_cmp_lt_i32_e32 vcc, v64, v68
	v_fmac_f32_e32 v109, v106, v106
	v_mul_f32_e32 v105, v103, v103
	v_fmac_f32_e32 v93, v90, v90
	v_mul_f32_e32 v89, v87, v87
	v_cndmask_b32_e32 v64, v185, v64, vcc
	v_add_f32_e32 v108, v108, v109
	v_fmac_f32_e32 v105, v102, v102
	v_add_f32_e32 v98, v98, v99
	v_add_f32_e32 v92, v92, v93
	v_fmac_f32_e32 v89, v86, v86
	v_lshlrev_b32_e32 v96, 2, v64
	v_add_f32_e32 v108, v113, v108
	v_add_f32_e32 v104, v104, v105
	v_add_f32_e32 v92, v98, v92
	v_add_f32_e32 v88, v88, v89
	ds_bpermute_b32 v69, v96, v67
	v_add_f32_e32 v104, v108, v104
	v_add_f32_e32 v100, v100, v101
	v_add_f32_e32 v88, v92, v88
	v_add_f32_e32 v84, v84, v85
	v_add_f32_e32 v100, v104, v100
	v_add_f32_e32 v84, v88, v84
	ds_bpermute_b32 v64, v96, v112
	ds_bpermute_b32 v65, v96, v100
	ds_bpermute_b32 v66, v96, v84
	s_waitcnt lgkmcnt(3)
	v_add_f32_e32 v67, v67, v69
	v_xor_b32_e32 v69, 32, v185
	v_cmp_lt_i32_e32 vcc, v69, v68
	s_waitcnt lgkmcnt(2)
	v_add_f32_e32 v64, v112, v64
	s_waitcnt lgkmcnt(1)
	v_add_f32_e32 v65, v100, v65
	v_cndmask_b32_e32 v68, v185, v69, vcc
	s_waitcnt lgkmcnt(0)
	v_add_f32_e32 v66, v84, v66
	v_lshlrev_b32_e32 v97, 2, v68
	ds_bpermute_b32 v68, v97, v64
	ds_bpermute_b32 v69, v97, v65
	ds_bpermute_b32 v70, v97, v66
	ds_bpermute_b32 v71, v97, v67
	v_lshl_add_u64 v[84:85], v[168:169], 2, s[12:13]
	v_mov_b32_e32 v244, v72
	v_mov_b32_e32 v245, v73
	v_mov_b32_e32 v246, v74
	v_mov_b32_e32 v247, v75
	v_mov_b32_dpp v244, v240 row_ror:8 row_mask:0xf bank_mask:0x3
	v_mov_b32_dpp v245, v241 row_ror:8 row_mask:0xf bank_mask:0x3
	v_mov_b32_dpp v246, v242 row_ror:8 row_mask:0xf bank_mask:0x3
	v_mov_b32_dpp v247, v243 row_ror:8 row_mask:0xf bank_mask:0x3
	v_mov_b32_dpp v240, v72 row_ror:8 row_mask:0xf bank_mask:0xc
	v_mov_b32_dpp v241, v73 row_ror:8 row_mask:0xf bank_mask:0xc
	v_mov_b32_dpp v242, v74 row_ror:8 row_mask:0xf bank_mask:0xc
	v_mov_b32_dpp v243, v75 row_ror:8 row_mask:0xf bank_mask:0xc
	v_lshl_add_u64 v[250:251], v[172:173], 0, v[254:255]
	v_lshl_add_u64 v[252:253], v[250:251], 0, s[98:99]
	global_store_dwordx4 v[250:251], v[240:243], off offset:512
	global_store_dwordx4 v[252:253], v[244:247], off offset:512
	v_ashrrev_i64 v[250:251], 1, v[254:255]
	v_lshl_add_u64 v[250:251], v[78:79], 0, v[250:251]
	v_lshl_add_u64 v[252:253], v[250:251], 0, s[100:101]
	v_cvt_pk_bf16_f32 v240, v240, v241
	v_cvt_pk_bf16_f32 v241, v242, v243
	v_cvt_pk_bf16_f32 v244, v244, v245
	v_cvt_pk_bf16_f32 v245, v246, v247
	global_store_dwordx2 v[250:251], v[240:241], off offset:256
	global_store_dwordx2 v[252:253], v[244:245], off offset:256
	s_nop 1
	v_cvt_pk_bf16_f32 v72, v72, v73
	v_cvt_pk_bf16_f32 v73, v74, v75
	s_and_saveexec_b64 s[6:7], s[2:3]
	s_cbranch_execz .LBB0_1478
	s_waitcnt lgkmcnt(3)
	v_add_f32_e32 v64, v64, v68
	s_waitcnt lgkmcnt(0)
	v_add_f32_e32 v67, v67, v71
	v_add_f32_e32 v66, v66, v70
	v_add_f32_e32 v65, v65, v69
	global_atomic_add_f32 v[84:85], v64, off
	global_atomic_add_f32 v[84:85], v65, off offset:64
	global_atomic_add_f32 v[84:85], v66, off offset:128
	global_atomic_add_f32 v[84:85], v67, off offset:192
.LBB0_1478:
	s_or_b64 exec, exec, s[6:7]
	v_add_u32_e32 v64, 0x80, v168
	v_ashrrev_i32_e32 v65, 31, v64
	v_lshlrev_b64 v[66:67], 13, v[64:65]
	v_lshl_add_u64 v[142:143], v[166:167], 0, v[66:67]
	global_load_dwordx4 v[98:101], v[142:143], off
	global_load_dwordx4 v[102:105], v[142:143], off offset:64
	global_load_dwordx4 v[106:109], v[142:143], off offset:512
	global_load_dwordx4 v[110:113], v[142:143], off offset:576
	v_add_u32_e32 v66, 0x90, v168
	v_ashrrev_i32_e32 v67, 31, v66
	s_waitcnt lgkmcnt(2)
	v_lshlrev_b64 v[68:69], 13, v[66:67]
	v_lshl_add_u64 v[92:93], v[166:167], 0, v[68:69]
	global_load_dwordx4 v[114:117], v[92:93], off
	global_load_dwordx4 v[118:121], v[92:93], off offset:64
	v_add_u32_e32 v90, 0xa0, v168
	v_add_u32_e32 v88, 0xb0, v168
	v_ashrrev_i32_e32 v91, 31, v90
	v_ashrrev_i32_e32 v89, 31, v88
	v_lshlrev_b64 v[68:69], 13, v[90:91]
	s_waitcnt lgkmcnt(0)
	v_lshlrev_b64 v[70:71], 13, v[88:89]
	v_lshlrev_b64 v[64:65], 11, v[64:65]
	v_lshlrev_b64 v[66:67], 11, v[66:67]
	v_lshl_add_u64 v[94:95], v[166:167], 0, v[68:69]
	v_lshl_add_u64 v[86:87], v[166:167], 0, v[70:71]
	v_lshl_add_u64 v[144:145], v[64:65], 0, v[164:165]
	v_lshl_add_u64 v[146:147], v[66:67], 0, v[164:165]
	global_load_dwordx4 v[122:125], v[92:93], off offset:512
	global_load_dwordx4 v[126:129], v[92:93], off offset:576
	global_load_dwordx4 v[130:133], v[94:95], off
	global_load_dwordx4 v[134:137], v[94:95], off offset:64
	global_load_dwordx4 v[138:141], v[94:95], off offset:512
	global_load_dwordx4 v[80:83], v[94:95], off offset:576
	global_load_dwordx4 v[76:79], v[86:87], off
	global_load_dwordx4 v[72:75], v[86:87], off offset:64
	global_load_dwordx4 v[68:71], v[86:87], off offset:512
	global_load_dwordx4 v[64:67], v[86:87], off offset:576
	v_lshl_add_u64 v[144:145], v[144:145], 1, s[10:11]
	s_waitcnt vmcnt(15)
	v_pk_add_f32 v[62:63], v[62:63], v[100:101]
	v_pk_add_f32 v[60:61], v[60:61], v[98:99]
	s_waitcnt vmcnt(14)
	v_pk_add_f32 v[58:59], v[58:59], v[104:105]
	v_pk_add_f32 v[56:57], v[56:57], v[102:103]
	s_waitcnt vmcnt(13)
	v_pk_add_f32 v[50:51], v[50:51], v[108:109]
	v_pk_add_f32 v[48:49], v[48:49], v[106:107]
	v_mov_b32_e32 v240, v60
	v_mov_b32_e32 v241, v61
	v_mov_b32_e32 v242, v62
	v_mov_b32_e32 v243, v63
	v_mul_f32_e32 v100, v61, v61
	v_mul_f32_e32 v101, v63, v63
	v_cvt_pk_bf16_f32 v98, v60, v61
	v_cvt_pk_bf16_f32 v99, v62, v63
	v_mul_f32_e32 v61, v57, v57
	v_mul_f32_e32 v63, v59, v59
	s_waitcnt vmcnt(12)
	v_pk_add_f32 v[46:47], v[46:47], v[112:113]
	v_pk_add_f32 v[44:45], v[44:45], v[110:111]
	v_mul_f32_e32 v102, v49, v49
	v_mul_f32_e32 v103, v51, v51
	v_fmac_f32_e32 v100, v60, v60
	v_fmac_f32_e32 v101, v62, v62
	v_fmac_f32_e32 v61, v56, v56
	v_fmac_f32_e32 v63, v58, v58
	v_mul_f32_e32 v104, v45, v45
	v_mul_f32_e32 v105, v47, v47
	v_mov_b32_e32 v244, v56
	v_mov_b32_e32 v245, v57
	v_mov_b32_e32 v246, v58
	v_mov_b32_e32 v247, v59
	v_mov_b32_dpp v244, v240 row_ror:8 row_mask:0xf bank_mask:0x3
	v_mov_b32_dpp v245, v241 row_ror:8 row_mask:0xf bank_mask:0x3
	v_mov_b32_dpp v246, v242 row_ror:8 row_mask:0xf bank_mask:0x3
	v_mov_b32_dpp v247, v243 row_ror:8 row_mask:0xf bank_mask:0x3
	v_mov_b32_dpp v240, v56 row_ror:8 row_mask:0xf bank_mask:0xc
	v_mov_b32_dpp v241, v57 row_ror:8 row_mask:0xf bank_mask:0xc
	v_mov_b32_dpp v242, v58 row_ror:8 row_mask:0xf bank_mask:0xc
	v_mov_b32_dpp v243, v59 row_ror:8 row_mask:0xf bank_mask:0xc
	v_lshl_add_u64 v[250:251], v[142:143], 0, v[254:255]
	v_lshl_add_u64 v[252:253], v[250:251], 0, s[98:99]
	global_store_dwordx4 v[250:251], v[240:243], off
	global_store_dwordx4 v[252:253], v[244:247], off
	v_ashrrev_i64 v[250:251], 1, v[254:255]
	v_lshl_add_u64 v[250:251], v[144:145], 0, v[250:251]
	v_lshl_add_u64 v[252:253], v[250:251], 0, s[100:101]
	v_cvt_pk_bf16_f32 v240, v240, v241
	v_cvt_pk_bf16_f32 v241, v242, v243
	v_cvt_pk_bf16_f32 v244, v244, v245
	v_cvt_pk_bf16_f32 v245, v246, v247
	global_store_dwordx2 v[250:251], v[240:241], off
	global_store_dwordx2 v[252:253], v[244:245], off
	v_fmac_f32_e32 v102, v48, v48
	v_fmac_f32_e32 v103, v50, v50
	v_cvt_pk_bf16_f32 v56, v56, v57
	v_cvt_pk_bf16_f32 v57, v58, v59
	v_add_f32_e32 v58, v100, v101
	v_add_f32_e32 v59, v61, v63
	v_fmac_f32_e32 v104, v44, v44
	v_fmac_f32_e32 v105, v46, v46
	v_mov_b32_e32 v240, v48
	v_mov_b32_e32 v241, v49
	v_mov_b32_e32 v242, v50
	v_mov_b32_e32 v243, v51
	v_add_f32_e32 v56, v102, v103
	s_waitcnt vmcnt(15)
	v_pk_add_f32 v[54:55], v[54:55], v[116:117]
	v_cvt_pk_bf16_f32 v48, v48, v49
	v_cvt_pk_bf16_f32 v49, v50, v51
	v_add_f32_e32 v51, v58, v59
	v_add_f32_e32 v50, v104, v105
	v_mov_b32_e32 v244, v44
	v_mov_b32_e32 v245, v45
	v_mov_b32_e32 v246, v46
	v_mov_b32_e32 v247, v47
	v_mov_b32_dpp v244, v240 row_ror:8 row_mask:0xf bank_mask:0x3
	v_mov_b32_dpp v245, v241 row_ror:8 row_mask:0xf bank_mask:0x3
	v_mov_b32_dpp v246, v242 row_ror:8 row_mask:0xf bank_mask:0x3
	v_mov_b32_dpp v247, v243 row_ror:8 row_mask:0xf bank_mask:0x3
	v_mov_b32_dpp v240, v44 row_ror:8 row_mask:0xf bank_mask:0xc
	v_mov_b32_dpp v241, v45 row_ror:8 row_mask:0xf bank_mask:0xc
	v_mov_b32_dpp v242, v46 row_ror:8 row_mask:0xf bank_mask:0xc
	v_mov_b32_dpp v243, v47 row_ror:8 row_mask:0xf bank_mask:0xc
	v_lshl_add_u64 v[250:251], v[142:143], 0, v[254:255]
	v_lshl_add_u64 v[252:253], v[250:251], 0, s[98:99]
	global_store_dwordx4 v[250:251], v[240:243], off offset:512
	global_store_dwordx4 v[252:253], v[244:247], off offset:512
	v_ashrrev_i64 v[250:251], 1, v[254:255]
	v_lshl_add_u64 v[250:251], v[144:145], 0, v[250:251]
	v_lshl_add_u64 v[252:253], v[250:251], 0, s[100:101]
	v_cvt_pk_bf16_f32 v240, v240, v241
	v_cvt_pk_bf16_f32 v241, v242, v243
	v_cvt_pk_bf16_f32 v244, v244, v245
	v_cvt_pk_bf16_f32 v245, v246, v247
	global_store_dwordx2 v[250:251], v[240:241], off offset:256
	global_store_dwordx2 v[252:253], v[244:245], off offset:256
	v_pk_add_f32 v[52:53], v[52:53], v[114:115]
	s_waitcnt vmcnt(17)
	v_pk_add_f32 v[40:41], v[40:41], v[118:119]
	v_cvt_pk_bf16_f32 v44, v44, v45
	v_cvt_pk_bf16_f32 v45, v46, v47
	v_add_f32_e32 v46, v51, v56
	v_mov_b32_e32 v240, v52
	v_mov_b32_e32 v241, v53
	v_mov_b32_e32 v242, v54
	v_mov_b32_e32 v243, v55
	v_add_f32_e32 v48, v46, v50
	v_cvt_pk_bf16_f32 v44, v52, v53
	v_lshl_add_u64 v[46:47], v[146:147], 1, s[10:11]
	v_cvt_pk_bf16_f32 v45, v54, v55
	v_pk_add_f32 v[42:43], v[42:43], v[120:121]
	v_mul_f32_e32 v44, v41, v41
	v_mov_b32_e32 v244, v40
	v_mov_b32_e32 v245, v41
	v_mov_b32_e32 v246, v42
	v_mov_b32_e32 v247, v43
	v_mov_b32_dpp v244, v240 row_ror:8 row_mask:0xf bank_mask:0x3
	v_mov_b32_dpp v245, v241 row_ror:8 row_mask:0xf bank_mask:0x3
	v_mov_b32_dpp v246, v242 row_ror:8 row_mask:0xf bank_mask:0x3
	v_mov_b32_dpp v247, v243 row_ror:8 row_mask:0xf bank_mask:0x3
	v_mov_b32_dpp v240, v40 row_ror:8 row_mask:0xf bank_mask:0xc
	v_mov_b32_dpp v241, v41 row_ror:8 row_mask:0xf bank_mask:0xc
	v_mov_b32_dpp v242, v42 row_ror:8 row_mask:0xf bank_mask:0xc
	v_mov_b32_dpp v243, v43 row_ror:8 row_mask:0xf bank_mask:0xc
	v_lshl_add_u64 v[250:251], v[92:93], 0, v[254:255]
	v_lshl_add_u64 v[252:253], v[250:251], 0, s[98:99]
	global_store_dwordx4 v[250:251], v[240:243], off
	global_store_dwordx4 v[252:253], v[244:247], off
	v_ashrrev_i64 v[250:251], 1, v[254:255]
	v_lshl_add_u64 v[250:251], v[46:47], 0, v[250:251]
	v_lshl_add_u64 v[252:253], v[250:251], 0, s[100:101]
	v_cvt_pk_bf16_f32 v240, v240, v241
	v_cvt_pk_bf16_f32 v241, v242, v243
	v_cvt_pk_bf16_f32 v244, v244, v245
	v_cvt_pk_bf16_f32 v245, v246, v247
	global_store_dwordx2 v[250:251], v[240:241], off
	global_store_dwordx2 v[252:253], v[244:245], off
	v_fmac_f32_e32 v44, v40, v40
	s_waitcnt vmcnt(20)
	v_pk_add_f32 v[36:37], v[36:37], v[122:123]
	v_cvt_pk_bf16_f32 v40, v40, v41
	v_cvt_pk_bf16_f32 v41, v42, v43
	v_pk_add_f32 v[38:39], v[38:39], v[124:125]
	v_mul_f32_e32 v40, v37, v37
	v_mov_b32_e32 v240, v36
	v_mov_b32_e32 v241, v37
	v_mov_b32_e32 v242, v38
	v_mov_b32_e32 v243, v39
	v_fmac_f32_e32 v40, v36, v36
	s_waitcnt vmcnt(20)
	v_pk_add_f32 v[32:33], v[32:33], v[126:127]
	v_cvt_pk_bf16_f32 v36, v36, v37
	v_cvt_pk_bf16_f32 v37, v38, v39
	v_pk_add_f32 v[34:35], v[34:35], v[128:129]
	v_mul_f32_e32 v36, v33, v33
	v_mov_b32_e32 v244, v32
	v_mov_b32_e32 v245, v33
	v_mov_b32_e32 v246, v34
	v_mov_b32_e32 v247, v35
	v_mov_b32_dpp v244, v240 row_ror:8 row_mask:0xf bank_mask:0x3
	v_mov_b32_dpp v245, v241 row_ror:8 row_mask:0xf bank_mask:0x3
	v_mov_b32_dpp v246, v242 row_ror:8 row_mask:0xf bank_mask:0x3
	v_mov_b32_dpp v247, v243 row_ror:8 row_mask:0xf bank_mask:0x3
	v_mov_b32_dpp v240, v32 row_ror:8 row_mask:0xf bank_mask:0xc
	v_mov_b32_dpp v241, v33 row_ror:8 row_mask:0xf bank_mask:0xc
	v_mov_b32_dpp v242, v34 row_ror:8 row_mask:0xf bank_mask:0xc
	v_mov_b32_dpp v243, v35 row_ror:8 row_mask:0xf bank_mask:0xc
	v_lshl_add_u64 v[250:251], v[92:93], 0, v[254:255]
	v_lshl_add_u64 v[252:253], v[250:251], 0, s[98:99]
	global_store_dwordx4 v[250:251], v[240:243], off offset:512
	global_store_dwordx4 v[252:253], v[244:247], off offset:512
	v_ashrrev_i64 v[250:251], 1, v[254:255]
	v_lshl_add_u64 v[250:251], v[46:47], 0, v[250:251]
	v_lshl_add_u64 v[252:253], v[250:251], 0, s[100:101]
	v_cvt_pk_bf16_f32 v240, v240, v241
	v_cvt_pk_bf16_f32 v241, v242, v243
	v_cvt_pk_bf16_f32 v244, v244, v245
	v_cvt_pk_bf16_f32 v245, v246, v247
	global_store_dwordx2 v[250:251], v[240:241], off offset:256
	global_store_dwordx2 v[252:253], v[244:245], off offset:256
	v_fmac_f32_e32 v36, v32, v32
	v_mul_f32_e32 v37, v35, v35
	v_cvt_pk_bf16_f32 v32, v32, v33
	v_cvt_pk_bf16_f32 v33, v34, v35
	v_lshlrev_b64 v[32:33], 11, v[90:91]
	s_waitcnt vmcnt(23)
	v_pk_add_f32 v[30:31], v[30:31], v[132:133]
	v_pk_add_f32 v[28:29], v[28:29], v[130:131]
	v_fmac_f32_e32 v37, v34, v34
	v_lshl_add_u64 v[32:33], v[32:33], 0, v[164:165]
	v_mul_f32_e32 v34, v29, v29
	v_mul_f32_e32 v35, v31, v31
	v_mov_b32_e32 v240, v28
	v_mov_b32_e32 v241, v29
	v_mov_b32_e32 v242, v30
	v_mov_b32_e32 v243, v31
	v_fmac_f32_e32 v34, v28, v28
	v_fmac_f32_e32 v35, v30, v30
	v_cvt_pk_bf16_f32 v28, v28, v29
	v_cvt_pk_bf16_f32 v29, v30, v31
	v_lshl_add_u64 v[30:31], v[32:33], 1, s[10:11]
	s_waitcnt vmcnt(22)
	v_pk_add_f32 v[24:25], v[24:25], v[134:135]
	v_pk_add_f32 v[26:27], v[26:27], v[136:137]
	v_mul_f32_e32 v28, v25, v25
	v_mov_b32_e32 v244, v24
	v_mov_b32_e32 v245, v25
	v_mov_b32_e32 v246, v26
	v_mov_b32_e32 v247, v27
	v_mov_b32_dpp v244, v240 row_ror:8 row_mask:0xf bank_mask:0x3
	v_mov_b32_dpp v245, v241 row_ror:8 row_mask:0xf bank_mask:0x3
	v_mov_b32_dpp v246, v242 row_ror:8 row_mask:0xf bank_mask:0x3
	v_mov_b32_dpp v247, v243 row_ror:8 row_mask:0xf bank_mask:0x3
	v_mov_b32_dpp v240, v24 row_ror:8 row_mask:0xf bank_mask:0xc
	v_mov_b32_dpp v241, v25 row_ror:8 row_mask:0xf bank_mask:0xc
	v_mov_b32_dpp v242, v26 row_ror:8 row_mask:0xf bank_mask:0xc
	v_mov_b32_dpp v243, v27 row_ror:8 row_mask:0xf bank_mask:0xc
	v_lshl_add_u64 v[250:251], v[94:95], 0, v[254:255]
	v_lshl_add_u64 v[252:253], v[250:251], 0, s[98:99]
	global_store_dwordx4 v[250:251], v[240:243], off
	global_store_dwordx4 v[252:253], v[244:247], off
	v_ashrrev_i64 v[250:251], 1, v[254:255]
	v_lshl_add_u64 v[250:251], v[30:31], 0, v[250:251]
	v_lshl_add_u64 v[252:253], v[250:251], 0, s[100:101]
	v_cvt_pk_bf16_f32 v240, v240, v241
	v_cvt_pk_bf16_f32 v241, v242, v243
	v_cvt_pk_bf16_f32 v244, v244, v245
	v_cvt_pk_bf16_f32 v245, v246, v247
	global_store_dwordx2 v[250:251], v[240:241], off
	global_store_dwordx2 v[252:253], v[244:245], off
	v_fmac_f32_e32 v28, v24, v24
	s_waitcnt vmcnt(24)
	v_pk_add_f32 v[20:21], v[20:21], v[138:139]
	v_cvt_pk_bf16_f32 v24, v24, v25
	v_cvt_pk_bf16_f32 v25, v26, v27
	v_pk_add_f32 v[22:23], v[22:23], v[140:141]
	v_mul_f32_e32 v24, v21, v21
	v_mov_b32_e32 v240, v20
	v_mov_b32_e32 v241, v21
	v_mov_b32_e32 v242, v22
	v_mov_b32_e32 v243, v23
	v_fmac_f32_e32 v24, v20, v20
	s_waitcnt vmcnt(24)
	v_pk_add_f32 v[16:17], v[16:17], v[80:81]
	v_cvt_pk_bf16_f32 v20, v20, v21
	v_cvt_pk_bf16_f32 v21, v22, v23
	v_pk_add_f32 v[18:19], v[18:19], v[82:83]
	v_mul_f32_e32 v20, v17, v17
	v_mov_b32_e32 v244, v16
	v_mov_b32_e32 v245, v17
	v_mov_b32_e32 v246, v18
	v_mov_b32_e32 v247, v19
	v_mov_b32_dpp v244, v240 row_ror:8 row_mask:0xf bank_mask:0x3
	v_mov_b32_dpp v245, v241 row_ror:8 row_mask:0xf bank_mask:0x3
	v_mov_b32_dpp v246, v242 row_ror:8 row_mask:0xf bank_mask:0x3
	v_mov_b32_dpp v247, v243 row_ror:8 row_mask:0xf bank_mask:0x3
	v_mov_b32_dpp v240, v16 row_ror:8 row_mask:0xf bank_mask:0xc
	v_mov_b32_dpp v241, v17 row_ror:8 row_mask:0xf bank_mask:0xc
	v_mov_b32_dpp v242, v18 row_ror:8 row_mask:0xf bank_mask:0xc
	v_mov_b32_dpp v243, v19 row_ror:8 row_mask:0xf bank_mask:0xc
	v_lshl_add_u64 v[250:251], v[94:95], 0, v[254:255]
	v_lshl_add_u64 v[252:253], v[250:251], 0, s[98:99]
	global_store_dwordx4 v[250:251], v[240:243], off offset:512
	global_store_dwordx4 v[252:253], v[244:247], off offset:512
	v_ashrrev_i64 v[250:251], 1, v[254:255]
	v_lshl_add_u64 v[250:251], v[30:31], 0, v[250:251]
	v_lshl_add_u64 v[252:253], v[250:251], 0, s[100:101]
	v_cvt_pk_bf16_f32 v240, v240, v241
	v_cvt_pk_bf16_f32 v241, v242, v243
	v_cvt_pk_bf16_f32 v244, v244, v245
	v_cvt_pk_bf16_f32 v245, v246, v247
	global_store_dwordx2 v[250:251], v[240:241], off offset:256
	global_store_dwordx2 v[252:253], v[244:245], off offset:256
	v_fmac_f32_e32 v20, v16, v16
	v_mul_f32_e32 v21, v19, v19
	v_cvt_pk_bf16_f32 v16, v16, v17
	v_cvt_pk_bf16_f32 v17, v18, v19
	v_lshlrev_b64 v[16:17], 11, v[88:89]
	s_waitcnt vmcnt(27)
	v_pk_add_f32 v[14:15], v[14:15], v[78:79]
	v_pk_add_f32 v[12:13], v[12:13], v[76:77]
	v_fmac_f32_e32 v21, v18, v18
	v_lshl_add_u64 v[16:17], v[16:17], 0, v[164:165]
	v_mul_f32_e32 v18, v13, v13
	v_mul_f32_e32 v19, v15, v15
	v_mov_b32_e32 v240, v12
	v_mov_b32_e32 v241, v13
	v_mov_b32_e32 v242, v14
	v_mov_b32_e32 v243, v15
	v_fmac_f32_e32 v18, v12, v12
	v_fmac_f32_e32 v19, v14, v14
	v_cvt_pk_bf16_f32 v12, v12, v13
	v_cvt_pk_bf16_f32 v13, v14, v15
	v_lshl_add_u64 v[14:15], v[16:17], 1, s[10:11]
	s_waitcnt vmcnt(26)
	v_pk_add_f32 v[8:9], v[8:9], v[72:73]
	v_pk_add_f32 v[10:11], v[10:11], v[74:75]
	v_mul_f32_e32 v12, v9, v9
	v_mov_b32_e32 v244, v8
	v_mov_b32_e32 v245, v9
	v_mov_b32_e32 v246, v10
	v_mov_b32_e32 v247, v11
	v_mov_b32_dpp v244, v240 row_ror:8 row_mask:0xf bank_mask:0x3
	v_mov_b32_dpp v245, v241 row_ror:8 row_mask:0xf bank_mask:0x3
	v_mov_b32_dpp v246, v242 row_ror:8 row_mask:0xf bank_mask:0x3
	v_mov_b32_dpp v247, v243 row_ror:8 row_mask:0xf bank_mask:0x3
	v_mov_b32_dpp v240, v8 row_ror:8 row_mask:0xf bank_mask:0xc
	v_mov_b32_dpp v241, v9 row_ror:8 row_mask:0xf bank_mask:0xc
	v_mov_b32_dpp v242, v10 row_ror:8 row_mask:0xf bank_mask:0xc
	v_mov_b32_dpp v243, v11 row_ror:8 row_mask:0xf bank_mask:0xc
	v_lshl_add_u64 v[250:251], v[86:87], 0, v[254:255]
	v_lshl_add_u64 v[252:253], v[250:251], 0, s[98:99]
	global_store_dwordx4 v[250:251], v[240:243], off
	global_store_dwordx4 v[252:253], v[244:247], off
	v_ashrrev_i64 v[250:251], 1, v[254:255]
	v_lshl_add_u64 v[250:251], v[14:15], 0, v[250:251]
	v_lshl_add_u64 v[252:253], v[250:251], 0, s[100:101]
	v_cvt_pk_bf16_f32 v240, v240, v241
	v_cvt_pk_bf16_f32 v241, v242, v243
	v_cvt_pk_bf16_f32 v244, v244, v245
	v_cvt_pk_bf16_f32 v245, v246, v247
	global_store_dwordx2 v[250:251], v[240:241], off
	global_store_dwordx2 v[252:253], v[244:245], off
	v_fmac_f32_e32 v12, v8, v8
	v_mul_f32_e32 v13, v11, v11
	v_cvt_pk_bf16_f32 v8, v8, v9
	v_cvt_pk_bf16_f32 v9, v10, v11
	s_waitcnt vmcnt(28)
	v_pk_add_f32 v[6:7], v[6:7], v[70:71]
	v_pk_add_f32 v[4:5], v[4:5], v[68:69]
	v_fmac_f32_e32 v13, v10, v10
	v_mul_f32_e32 v8, v5, v5
	v_mul_f32_e32 v9, v7, v7
	v_add_f32_e32 v18, v18, v19
	v_add_f32_e32 v12, v12, v13
	v_fmac_f32_e32 v8, v4, v4
	v_fmac_f32_e32 v9, v6, v6
	v_mul_f32_e32 v106, v53, v53
	v_mul_f32_e32 v107, v55, v55
	v_mul_f32_e32 v45, v43, v43
	v_mul_f32_e32 v29, v27, v27
	v_add_f32_e32 v12, v18, v12
	v_add_f32_e32 v8, v8, v9
	v_fmac_f32_e32 v106, v52, v52
	v_fmac_f32_e32 v107, v54, v54
	v_fmac_f32_e32 v45, v42, v42
	v_mul_f32_e32 v41, v39, v39
	v_fmac_f32_e32 v29, v26, v26
	v_mul_f32_e32 v25, v23, v23
	v_add_f32_e32 v12, v12, v8
	s_waitcnt vmcnt(28)
	v_pk_add_f32 v[10:11], v[2:3], v[66:67]
	v_pk_add_f32 v[8:9], v[0:1], v[64:65]
	v_add_f32_e32 v49, v106, v107
	v_add_f32_e32 v44, v44, v45
	v_fmac_f32_e32 v41, v38, v38
	v_add_f32_e32 v34, v34, v35
	v_add_f32_e32 v28, v28, v29
	v_fmac_f32_e32 v25, v22, v22
	v_mul_f32_e32 v0, v9, v9
	v_mul_f32_e32 v1, v11, v11
	v_add_f32_e32 v44, v49, v44
	v_add_f32_e32 v40, v40, v41
	v_add_f32_e32 v28, v34, v28
	v_add_f32_e32 v24, v24, v25
	v_fmac_f32_e32 v0, v8, v8
	v_fmac_f32_e32 v1, v10, v10
	v_add_f32_e32 v40, v44, v40
	v_add_f32_e32 v36, v36, v37
	v_add_f32_e32 v24, v28, v24
	v_add_f32_e32 v20, v20, v21
	v_add_f32_e32 v0, v0, v1
	v_add_f32_e32 v36, v40, v36
	v_add_f32_e32 v20, v24, v20
	v_add_f32_e32 v3, v12, v0
	v_mov_b32_e32 v240, v4
	v_mov_b32_e32 v241, v5
	v_mov_b32_e32 v242, v6
	v_mov_b32_e32 v243, v7
	ds_bpermute_b32 v0, v96, v48
	ds_bpermute_b32 v1, v96, v36
	v_cvt_pk_bf16_f32 v4, v4, v5
	v_cvt_pk_bf16_f32 v5, v6, v7
	ds_bpermute_b32 v2, v96, v20
	ds_bpermute_b32 v6, v96, v3
	s_waitcnt lgkmcnt(3)
	v_add_f32_e32 v0, v48, v0
	s_waitcnt lgkmcnt(2)
	v_add_f32_e32 v1, v36, v1
	s_waitcnt lgkmcnt(1)
	v_add_f32_e32 v2, v20, v2
	s_waitcnt lgkmcnt(0)
	v_add_f32_e32 v4, v3, v6
	ds_bpermute_b32 v3, v97, v0
	ds_bpermute_b32 v5, v97, v1
	ds_bpermute_b32 v6, v97, v2
	ds_bpermute_b32 v7, v97, v4
	v_mov_b32_e32 v244, v8
	v_mov_b32_e32 v245, v9
	v_mov_b32_e32 v246, v10
	v_mov_b32_e32 v247, v11
	v_mov_b32_dpp v244, v240 row_ror:8 row_mask:0xf bank_mask:0x3
	v_mov_b32_dpp v245, v241 row_ror:8 row_mask:0xf bank_mask:0x3
	v_mov_b32_dpp v246, v242 row_ror:8 row_mask:0xf bank_mask:0x3
	v_mov_b32_dpp v247, v243 row_ror:8 row_mask:0xf bank_mask:0x3
	v_mov_b32_dpp v240, v8 row_ror:8 row_mask:0xf bank_mask:0xc
	v_mov_b32_dpp v241, v9 row_ror:8 row_mask:0xf bank_mask:0xc
	v_mov_b32_dpp v242, v10 row_ror:8 row_mask:0xf bank_mask:0xc
	v_mov_b32_dpp v243, v11 row_ror:8 row_mask:0xf bank_mask:0xc
	v_lshl_add_u64 v[250:251], v[86:87], 0, v[254:255]
	v_lshl_add_u64 v[252:253], v[250:251], 0, s[98:99]
	global_store_dwordx4 v[250:251], v[240:243], off offset:512
	global_store_dwordx4 v[252:253], v[244:247], off offset:512
	v_ashrrev_i64 v[250:251], 1, v[254:255]
	v_lshl_add_u64 v[250:251], v[14:15], 0, v[250:251]
	v_lshl_add_u64 v[252:253], v[250:251], 0, s[100:101]
	v_cvt_pk_bf16_f32 v240, v240, v241
	v_cvt_pk_bf16_f32 v241, v242, v243
	v_cvt_pk_bf16_f32 v244, v244, v245
	v_cvt_pk_bf16_f32 v245, v246, v247
	global_store_dwordx2 v[250:251], v[240:241], off offset:256
	global_store_dwordx2 v[252:253], v[244:245], off offset:256
	s_nop 1
	v_cvt_pk_bf16_f32 v8, v8, v9
	v_cvt_pk_bf16_f32 v9, v10, v11
	s_and_saveexec_b64 s[6:7], s[2:3]
	s_cbranch_execz .LBB0_1480
	s_waitcnt lgkmcnt(3)
	v_add_f32_e32 v0, v0, v3
	s_waitcnt lgkmcnt(0)
	v_add_f32_e32 v4, v4, v7
	v_add_f32_e32 v2, v2, v6
	v_add_f32_e32 v1, v1, v5
	global_atomic_add_f32 v[84:85], v0, off offset:512
	global_atomic_add_f32 v[84:85], v1, off offset:576
	global_atomic_add_f32 v[84:85], v2, off offset:640
	global_atomic_add_f32 v[84:85], v4, off offset:704
